# XN image layout for all three norms: INM A operand contiguous per K-step; g4 gate-A DMA reads the image (per-lane source offsets), same line count
# baseline (speedup 1.0000x reference)
.LBB0_87:
	v_ashrrev_i32_e32 v129, 31, v128
	v_lshlrev_b64 v[84:85], 12, v[128:129]
	v_lshl_add_u64 v[84:85], v[132:133], 0, v[84:85]
	s_waitcnt lgkmcnt(2)
	s_waitcnt vmcnt(0)
	v_mov_b32_e32 v124, v192
	v_mov_b32_e32 v125, v193
	v_mov_b32_e32 v126, v194
	v_mov_b32_e32 v127, v195
	s_waitcnt lgkmcnt(0)
	v_mov_b32_e32 v164, v196
	v_mov_b32_e32 v165, v197
	v_mov_b32_e32 v166, v198
	v_mov_b32_e32 v167, v199
	v_mov_b32_e32 v174, v204
	v_mov_b32_e32 v175, v205
	v_mov_b32_e32 v176, v206
	v_mov_b32_e32 v177, v207
	v_mov_b32_e32 v178, v208
	v_mov_b32_e32 v179, v209
	v_mov_b32_e32 v180, v210
	v_mov_b32_e32 v181, v211
	v_add_u32_e32 v212, s81, v128
	v_min_i32_e32 v212, s76, v212
	v_ashrrev_i32_e32 v213, 31, v212
	v_lshlrev_b64 v[212:213], 12, v[212:213]
	v_lshl_add_u64 v[212:213], v[132:133], 0, v[212:213]
	global_load_dwordx4 v[192:195], v[212:213], off
	global_load_dwordx4 v[196:199], v[212:213], off offset:1024
	global_load_dwordx4 v[204:207], v[212:213], off offset:2048
	global_load_dwordx4 v[208:211], v[212:213], off offset:3072
	v_mov_b32_e32 v96, v125
	v_mov_b32_e32 v97, v165
	v_mov_b32_e32 v84, v124
	v_mov_b32_e32 v85, v164
	v_mov_b32_e32 v182, v175
	v_mov_b32_e32 v183, v179
	v_pk_mul_f32 v[96:97], v[96:97], v[96:97]
	v_mov_b32_e32 v108, v126
	v_mov_b32_e32 v109, v166
	v_mov_b32_e32 v162, v174
	v_mov_b32_e32 v163, v178
	v_pk_mul_f32 v[182:183], v[182:183], v[182:183]
	v_pk_fma_f32 v[84:85], v[84:85], v[84:85], v[96:97]
	v_mov_b32_e32 v120, v127
	v_mov_b32_e32 v121, v167
	v_mov_b32_e32 v184, v176
	v_mov_b32_e32 v185, v180
	v_pk_fma_f32 v[96:97], v[162:163], v[162:163], v[182:183]
	v_pk_fma_f32 v[84:85], v[108:109], v[108:109], v[84:85]
	v_mov_b32_e32 v186, v177
	v_mov_b32_e32 v187, v181
	v_pk_fma_f32 v[96:97], v[184:185], v[184:185], v[96:97]
	v_pk_fma_f32 v[84:85], v[120:121], v[120:121], v[84:85]
	v_pk_fma_f32 v[96:97], v[186:187], v[186:187], v[96:97]
	v_add_f32_e32 v84, v84, v85
	v_add_f32_e32 v84, v84, v96
	v_add_f32_e32 v84, v84, v97
	ds_bpermute_b32 v85, v168, v84
	v_mov_b32_e32 v108, v125
	v_mov_b32_e32 v121, v166
	v_mov_b32_e32 v166, v165
	s_waitcnt lgkmcnt(0)
	v_add_f32_e32 v84, v84, v85
	ds_bpermute_b32 v85, v169, v84
	s_waitcnt lgkmcnt(0)
	v_add_f32_e32 v96, v84, v85
	ds_bpermute_b32 v97, v170, v96
	v_readlane_b32 s96, v253, 4
	v_readlane_b32 s97, v253, 5
	v_and_b32_e32 v85, 63, v216
	v_lshrrev_b32_e32 v84, 3, v85
	v_lshlrev_b32_e32 v84, 13, v84
	v_and_b32_e32 v85, 7, v85
	v_lshl_or_b32 v84, v85, 3, v84
	v_and_b32_e32 v85, 8, v128
	v_mul_u32_u24_e32 v85, 6, v85
	v_xor_b32_e32 v84, v84, v85
	v_and_b32_e32 v85, 0x7f, v128
	v_lshl_add_u32 v84, v85, 6, v84
	v_lshrrev_b32_e32 v85, 7, v128
	v_lshl_add_u32 v84, v85, 18, v84
	s_waitcnt lgkmcnt(0)
	v_add_f32_e32 v109, v96, v97
	ds_bpermute_b32 v120, v171, v109
	v_mov_b32_e32 v96, v124
	v_mov_b32_e32 v97, v126
	s_waitcnt lgkmcnt(0)
	v_add_f32_e32 v124, v109, v120
	ds_bpermute_b32 v125, v172, v124
	v_mov_b32_e32 v109, v127
	v_mov_b32_e32 v120, v164
	s_waitcnt lgkmcnt(0)
	v_add_f32_e32 v126, v124, v125
	ds_bpermute_b32 v127, v173, v126
	v_mov_b32_e32 v124, v174
	v_mov_b32_e32 v125, v176
	v_mov_b32_e32 v174, v175
	v_mov_b32_e32 v175, v177
	s_waitcnt lgkmcnt(0)
	v_add_f32_e32 v126, v126, v127
	v_fmamk_f32 v126, v126, 0x3a800000, v217
	v_mul_f32_e32 v127, 0x4b800000, v126
	v_cmp_gt_f32_e64 s[8:9], s75, v126
	v_mov_b32_e32 v176, v178
	v_mov_b32_e32 v177, v180
	v_cndmask_b32_e64 v126, v126, v127, s[8:9]
	v_rsq_f32_e32 v126, v126
	v_mov_b32_e32 v180, v179
	v_mul_f32_e32 v127, 0x45800000, v126
	v_cndmask_b32_e64 v126, v126, v127, s[8:9]
	v_pk_mul_f32 v[162:163], v[0:1], v[126:127] op_sel_hi:[1,0]
	v_pk_mul_f32 v[164:165], v[114:115], v[126:127] op_sel_hi:[1,0]
	v_pk_mul_f32 v[178:179], v[4:5], v[126:127] op_sel_hi:[1,0]
	v_pk_mul_f32 v[182:183], v[2:3], v[126:127] op_sel_hi:[1,0]
	v_pk_mul_f32 v[186:187], v[96:97], v[162:163]
	v_pk_mul_f32 v[96:97], v[6:7], v[126:127] op_sel_hi:[1,0]
	v_pk_mul_f32 v[164:165], v[108:109], v[164:165]
	v_pk_mul_f32 v[108:109], v[12:13], v[126:127] op_sel_hi:[1,0]
	v_pk_mul_f32 v[188:189], v[10:11], v[126:127] op_sel_hi:[1,0]
	v_pk_mul_f32 v[184:185], v[8:9], v[126:127] op_sel_hi:[1,0]
	v_pk_mul_f32 v[162:163], v[120:121], v[178:179]
	v_pk_mul_f32 v[126:127], v[166:167], v[182:183]
	v_pk_mul_f32 v[120:121], v[174:175], v[96:97]
	v_pk_mul_f32 v[96:97], v[176:177], v[108:109]
	v_pk_mul_f32 v[108:109], v[180:181], v[188:189]
	v_and_b32_sdwa v181, v186, v232 dst_sel:DWORD dst_unused:UNUSED_PAD src0_sel:WORD_1 src1_sel:DWORD
	v_and_b32_sdwa v182, v165, v232 dst_sel:DWORD dst_unused:UNUSED_PAD src0_sel:WORD_1 src1_sel:DWORD
	v_and_b32_sdwa v183, v164, v232 dst_sel:DWORD dst_unused:UNUSED_PAD src0_sel:WORD_1 src1_sel:DWORD
	v_and_b32_sdwa v180, v187, v232 dst_sel:DWORD dst_unused:UNUSED_PAD src0_sel:WORD_1 src1_sel:DWORD
	v_pk_mul_f32 v[166:167], v[20:21], v[164:165] op_sel_hi:[1,0]
	v_pk_mul_f32 v[174:175], v[164:165], v[36:37] op_sel_hi:[0,1]
	v_pk_mul_f32 v[176:177], v[164:165], v[52:53] op_sel_hi:[0,1]
	v_pk_mul_f32 v[178:179], v[164:165], v[68:69] op_sel_hi:[0,1]
	v_add3_u32 v190, v186, v181, s69
	v_add3_u32 v181, v165, v182, s69
	v_add3_u32 v182, v164, v183, s69
	v_pk_mul_f32 v[124:125], v[124:125], v[184:185]
	v_and_b32_sdwa v184, v163, v232 dst_sel:DWORD dst_unused:UNUSED_PAD src0_sel:WORD_1 src1_sel:DWORD
	v_and_b32_sdwa v185, v162, v232 dst_sel:DWORD dst_unused:UNUSED_PAD src0_sel:WORD_1 src1_sel:DWORD
	v_and_b32_sdwa v188, v127, v232 dst_sel:DWORD dst_unused:UNUSED_PAD src0_sel:WORD_1 src1_sel:DWORD
	v_and_b32_sdwa v189, v126, v232 dst_sel:DWORD dst_unused:UNUSED_PAD src0_sel:WORD_1 src1_sel:DWORD
	v_add3_u32 v180, v187, v180, s69
	v_pk_fma_f32 v[166:167], v[80:81], v[186:187], v[166:167] op_sel_hi:[1,0,1]
	v_pk_fma_f32 v[174:175], v[186:187], v[92:93], v[174:175] op_sel_hi:[0,1,1]
	v_pk_fma_f32 v[176:177], v[186:187], v[104:105], v[176:177] op_sel_hi:[0,1,1]
	v_pk_fma_f32 v[178:179], v[186:187], v[116:117], v[178:179] op_sel_hi:[0,1,1]
	v_and_b32_e32 v181, 0xffff0000, v181
	v_and_b32_e32 v182, 0xffff0000, v182
	v_pk_fma_f32 v[166:167], v[16:17], v[186:187], v[166:167] op_sel:[0,1,0]
	v_pk_fma_f32 v[174:175], v[186:187], v[30:31], v[174:175] op_sel:[1,0,0]
	v_pk_fma_f32 v[176:177], v[186:187], v[46:47], v[176:177] op_sel:[1,0,0]
	v_pk_fma_f32 v[178:179], v[186:187], v[62:63], v[178:179] op_sel:[1,0,0]
	v_and_b32_sdwa v187, v124, v232 dst_sel:DWORD dst_unused:UNUSED_PAD src0_sel:WORD_1 src1_sel:DWORD
	v_or_b32_sdwa v181, v181, v180 dst_sel:DWORD dst_unused:UNUSED_PAD src0_sel:DWORD src1_sel:WORD_1
	v_or_b32_sdwa v180, v182, v190 dst_sel:DWORD dst_unused:UNUSED_PAD src0_sel:DWORD src1_sel:WORD_1
	v_and_b32_sdwa v190, v121, v232 dst_sel:DWORD dst_unused:UNUSED_PAD src0_sel:WORD_1 src1_sel:DWORD
	v_and_b32_sdwa v191, v120, v232 dst_sel:DWORD dst_unused:UNUSED_PAD src0_sel:WORD_1 src1_sel:DWORD
	v_add3_u32 v182, v162, v185, s69
	v_add3_u32 v183, v163, v184, s69
	v_add3_u32 v184, v127, v188, s69
	v_add3_u32 v185, v126, v189, s69
	v_and_b32_sdwa v186, v125, v232 dst_sel:DWORD dst_unused:UNUSED_PAD src0_sel:WORD_1 src1_sel:DWORD
	v_and_b32_e32 v184, 0xffff0000, v184
	v_and_b32_e32 v185, 0xffff0000, v185
	v_add3_u32 v188, v124, v187, s69
	v_add3_u32 v187, v121, v190, s69
	v_add3_u32 v189, v120, v191, s69
	v_or_b32_sdwa v183, v184, v183 dst_sel:DWORD dst_unused:UNUSED_PAD src0_sel:DWORD src1_sel:WORD_1
	v_or_b32_sdwa v182, v185, v182 dst_sel:DWORD dst_unused:UNUSED_PAD src0_sel:DWORD src1_sel:WORD_1
	v_pk_mul_f32 v[184:185], v[126:127], v[24:25] op_sel_hi:[0,1]
	v_add3_u32 v186, v125, v186, s69
	v_and_b32_e32 v187, 0xffff0000, v187
	v_and_b32_e32 v189, 0xffff0000, v189
	global_store_dwordx2 v84, v[180:181], s[96:97]
	v_mov_b32_e32 v180, v124
	v_mov_b32_e32 v181, v120
	v_or_b32_sdwa v187, v187, v186 dst_sel:DWORD dst_unused:UNUSED_PAD src0_sel:DWORD src1_sel:WORD_1
	v_or_b32_sdwa v186, v189, v188 dst_sel:DWORD dst_unused:UNUSED_PAD src0_sel:DWORD src1_sel:WORD_1
	v_mov_b32_e32 v188, v120
	v_mov_b32_e32 v189, v124
	v_pk_fma_f32 v[184:185], v[162:163], v[26:27], v[184:185] op_sel_hi:[0,1,1]
	v_add_u32_e32 v84, 0x10000, v84
	global_store_dwordx2 v84, v[182:183], s[96:97]
	v_pk_mul_f32 v[182:183], v[180:181], v[28:29]
	v_pk_fma_f32 v[166:167], v[22:23], v[164:165], v[166:167] op_sel:[0,1,0]
	v_pk_fma_f32 v[184:185], v[162:163], v[18:19], v[184:185] op_sel:[1,0,0]
	v_pk_fma_f32 v[182:183], v[188:189], v[38:39], v[182:183]
	v_pk_add_f32 v[166:167], v[166:167], 0 op_sel_hi:[1,0]
	v_pk_fma_f32 v[184:185], v[126:127], v[134:135], v[184:185] op_sel:[1,0,0]
	v_pk_fma_f32 v[182:183], v[124:125], v[136:137], v[182:183] op_sel:[1,0,0]
	v_pk_add_f32 v[166:167], v[166:167], v[184:185]
	v_pk_fma_f32 v[182:183], v[120:121], v[82:83], v[182:183] op_sel:[1,0,0]
	v_mov_b32_e32 v184, v96
	v_mov_b32_e32 v185, v108
	v_add_u32_e32 v84, 0x10000, v84
	global_store_dwordx2 v84, v[186:187], s[96:97]
	v_pk_add_f32 v[166:167], v[166:167], v[182:183]
	v_mov_b32_e32 v182, v108
	v_mov_b32_e32 v183, v96
	v_pk_mul_f32 v[186:187], v[184:185], v[76:77]
	v_pk_fma_f32 v[174:175], v[164:165], v[32:33], v[174:175] op_sel:[1,0,0]
	v_pk_fma_f32 v[186:187], v[182:183], v[138:139], v[186:187]
	v_pk_add_f32 v[174:175], v[174:175], 0 op_sel_hi:[1,0]
	v_pk_fma_f32 v[186:187], v[96:97], v[140:141], v[186:187] op_sel:[1,0,0]
	v_pk_fma_f32 v[176:177], v[164:165], v[48:49], v[176:177] op_sel:[1,0,0]
	v_pk_fma_f32 v[186:187], v[108:109], v[86:87], v[186:187] op_sel:[1,0,0]
	v_pk_add_f32 v[176:177], v[176:177], 0 op_sel_hi:[1,0]
	v_pk_add_f32 v[166:167], v[166:167], v[186:187]
	ds_bpermute_b32 v186, v168, v166
	ds_bpermute_b32 v187, v168, v167
	v_pk_fma_f32 v[164:165], v[164:165], v[64:65], v[178:179] op_sel:[1,0,0]
	v_pk_mul_f32 v[178:179], v[126:127], v[72:73] op_sel_hi:[0,1]
	v_pk_fma_f32 v[178:179], v[162:163], v[74:75], v[178:179] op_sel_hi:[0,1,1]
	v_pk_add_f32 v[164:165], v[164:165], 0 op_sel_hi:[1,0]
	s_waitcnt lgkmcnt(0)
	v_pk_add_f32 v[166:167], v[166:167], v[186:187]
	ds_bpermute_b32 v186, v169, v166
	ds_bpermute_b32 v187, v169, v167
	s_waitcnt lgkmcnt(0)
	v_pk_add_f32 v[166:167], v[166:167], v[186:187]
	ds_bpermute_b32 v186, v170, v166
	ds_bpermute_b32 v187, v170, v167
	s_waitcnt lgkmcnt(0)
	v_pk_add_f32 v[166:167], v[166:167], v[186:187]
	ds_bpermute_b32 v186, v171, v166
	ds_bpermute_b32 v187, v171, v167
	s_waitcnt lgkmcnt(0)
	v_pk_add_f32 v[166:167], v[166:167], v[186:187]
	ds_bpermute_b32 v186, v172, v166
	ds_bpermute_b32 v187, v172, v167
	s_waitcnt lgkmcnt(0)
	v_pk_add_f32 v[166:167], v[166:167], v[186:187]
	v_pk_mul_f32 v[186:187], v[126:127], v[40:41] op_sel_hi:[0,1]
	v_pk_fma_f32 v[186:187], v[162:163], v[42:43], v[186:187] op_sel_hi:[0,1,1]
	v_pk_fma_f32 v[186:187], v[162:163], v[34:35], v[186:187] op_sel:[1,0,0]
	s_nop 0
	v_pk_fma_f32 v[186:187], v[126:127], v[78:79], v[186:187] op_sel:[1,0,0]
	s_nop 0
	v_pk_add_f32 v[174:175], v[174:175], v[186:187]
	v_pk_mul_f32 v[186:187], v[180:181], v[44:45]
	s_nop 0
	v_pk_fma_f32 v[186:187], v[188:189], v[54:55], v[186:187]
	s_nop 0
	v_pk_fma_f32 v[186:187], v[124:125], v[142:143], v[186:187] op_sel:[1,0,0]
	s_nop 0
	v_pk_fma_f32 v[186:187], v[120:121], v[94:95], v[186:187] op_sel:[1,0,0]
	s_nop 0
	v_pk_add_f32 v[174:175], v[174:175], v[186:187]
	v_pk_mul_f32 v[186:187], v[184:185], v[88:89]
	s_nop 0
	v_pk_fma_f32 v[186:187], v[182:183], v[144:145], v[186:187]
	s_nop 0
	v_pk_fma_f32 v[186:187], v[96:97], v[146:147], v[186:187] op_sel:[1,0,0]
	s_nop 0
	v_pk_fma_f32 v[186:187], v[108:109], v[98:99], v[186:187] op_sel:[1,0,0]
	s_nop 0
	v_pk_add_f32 v[174:175], v[174:175], v[186:187]
	ds_bpermute_b32 v186, v168, v174
	ds_bpermute_b32 v187, v168, v175
	s_waitcnt lgkmcnt(0)
	v_pk_add_f32 v[174:175], v[174:175], v[186:187]
	ds_bpermute_b32 v186, v169, v174
	ds_bpermute_b32 v187, v169, v175
	s_waitcnt lgkmcnt(0)
	v_pk_add_f32 v[174:175], v[174:175], v[186:187]
	ds_bpermute_b32 v186, v170, v174
	ds_bpermute_b32 v187, v170, v175
	s_waitcnt lgkmcnt(0)
	v_pk_add_f32 v[174:175], v[174:175], v[186:187]
	ds_bpermute_b32 v186, v171, v174
	ds_bpermute_b32 v187, v171, v175
	s_waitcnt lgkmcnt(0)
	v_pk_add_f32 v[174:175], v[174:175], v[186:187]
	v_pk_mul_f32 v[186:187], v[126:127], v[56:57] op_sel_hi:[0,1]
	v_pk_fma_f32 v[186:187], v[162:163], v[58:59], v[186:187] op_sel_hi:[0,1,1]
	v_pk_fma_f32 v[186:187], v[162:163], v[50:51], v[186:187] op_sel:[1,0,0]
	v_pk_fma_f32 v[162:163], v[162:163], v[66:67], v[178:179] op_sel:[1,0,0]
	v_pk_fma_f32 v[186:187], v[126:127], v[90:91], v[186:187] op_sel:[1,0,0]
	v_and_b32_sdwa v178, v109, v232 dst_sel:DWORD dst_unused:UNUSED_PAD src0_sel:WORD_1 src1_sel:DWORD
	v_pk_add_f32 v[176:177], v[176:177], v[186:187]
	v_pk_mul_f32 v[186:187], v[180:181], v[60:61]
	v_and_b32_sdwa v179, v108, v232 dst_sel:DWORD dst_unused:UNUSED_PAD src0_sel:WORD_1 src1_sel:DWORD
	v_pk_fma_f32 v[186:187], v[188:189], v[70:71], v[186:187]
	v_add3_u32 v178, v109, v178, s69
	v_pk_fma_f32 v[186:187], v[124:125], v[148:149], v[186:187] op_sel:[1,0,0]
	v_add3_u32 v190, v108, v179, s69
	v_pk_fma_f32 v[186:187], v[120:121], v[106:107], v[186:187] op_sel:[1,0,0]
	v_and_b32_e32 v191, 0xffff0000, v178
	v_pk_add_f32 v[176:177], v[176:177], v[186:187]
	v_pk_mul_f32 v[186:187], v[184:185], v[100:101]
	v_pk_mul_f32 v[178:179], v[180:181], v[14:15]
	v_pk_fma_f32 v[186:187], v[182:183], v[150:151], v[186:187]
	v_pk_fma_f32 v[178:179], v[188:189], v[160:161], v[178:179]
	v_pk_fma_f32 v[186:187], v[96:97], v[152:153], v[186:187] op_sel:[1,0,0]
	v_pk_fma_f32 v[124:125], v[124:125], v[154:155], v[178:179] op_sel:[1,0,0]
	v_pk_fma_f32 v[186:187], v[108:109], v[110:111], v[186:187] op_sel:[1,0,0]
	v_pk_fma_f32 v[120:121], v[120:121], v[118:119], v[124:125] op_sel:[1,0,0]
	v_pk_mul_f32 v[124:125], v[184:185], v[112:113]
	v_pk_add_f32 v[176:177], v[176:177], v[186:187]
	v_and_b32_sdwa v186, v97, v232 dst_sel:DWORD dst_unused:UNUSED_PAD src0_sel:WORD_1 src1_sel:DWORD
	v_and_b32_sdwa v187, v96, v232 dst_sel:DWORD dst_unused:UNUSED_PAD src0_sel:WORD_1 src1_sel:DWORD
	v_pk_fma_f32 v[162:163], v[126:127], v[102:103], v[162:163] op_sel:[1,0,0]
	v_pk_fma_f32 v[124:125], v[182:183], v[156:157], v[124:125]
	v_add3_u32 v187, v96, v187, s69
	v_add3_u32 v186, v97, v186, s69
	v_pk_add_f32 v[162:163], v[164:165], v[162:163]
	v_pk_fma_f32 v[96:97], v[96:97], v[158:159], v[124:125] op_sel:[1,0,0]
	v_pk_add_f32 v[120:121], v[162:163], v[120:121]
	v_pk_fma_f32 v[96:97], v[108:109], v[122:123], v[96:97] op_sel:[1,0,0]
	ds_bpermute_b32 v164, v168, v176
	v_pk_add_f32 v[96:97], v[120:121], v[96:97]
	ds_bpermute_b32 v165, v168, v177
	ds_bpermute_b32 v108, v168, v96
	ds_bpermute_b32 v109, v168, v97
	ds_bpermute_b32 v120, v172, v174
	ds_bpermute_b32 v121, v172, v175
	s_waitcnt lgkmcnt(4)
	v_pk_add_f32 v[124:125], v[176:177], v[164:165]
	ds_bpermute_b32 v162, v169, v124
	s_waitcnt lgkmcnt(3)
	v_pk_add_f32 v[96:97], v[96:97], v[108:109]
	ds_bpermute_b32 v163, v169, v125
	ds_bpermute_b32 v108, v169, v96
	ds_bpermute_b32 v109, v169, v97
	ds_bpermute_b32 v126, v173, v166
	ds_bpermute_b32 v127, v173, v167
	s_waitcnt lgkmcnt(4)
	v_pk_add_f32 v[124:125], v[124:125], v[162:163]
	ds_bpermute_b32 v162, v170, v124
	s_waitcnt lgkmcnt(3)
	v_pk_add_f32 v[108:109], v[96:97], v[108:109]
	ds_bpermute_b32 v163, v170, v125
	ds_bpermute_b32 v164, v170, v108
	ds_bpermute_b32 v165, v170, v109
	v_pk_add_f32 v[96:97], v[174:175], v[120:121]
	v_and_b32_e32 v174, 0xffff0000, v190
	s_waitcnt lgkmcnt(2)
	v_pk_add_f32 v[120:121], v[124:125], v[162:163]
	ds_bpermute_b32 v124, v171, v120
	s_waitcnt lgkmcnt(1)
	v_pk_add_f32 v[162:163], v[108:109], v[164:165]
	ds_bpermute_b32 v125, v171, v121
	ds_bpermute_b32 v164, v171, v162
	ds_bpermute_b32 v165, v171, v163
	ds_bpermute_b32 v108, v173, v96
	ds_bpermute_b32 v109, v173, v97
	s_waitcnt lgkmcnt(4)
	v_pk_add_f32 v[120:121], v[120:121], v[124:125]
	ds_bpermute_b32 v124, v172, v120
	s_waitcnt lgkmcnt(3)
	v_pk_add_f32 v[162:163], v[162:163], v[164:165]
	ds_bpermute_b32 v125, v172, v121
	ds_bpermute_b32 v164, v172, v162
	ds_bpermute_b32 v165, v172, v163
	v_or_b32_sdwa v175, v191, v186 dst_sel:DWORD dst_unused:UNUSED_PAD src0_sel:DWORD src1_sel:WORD_1
	v_or_b32_sdwa v174, v174, v187 dst_sel:DWORD dst_unused:UNUSED_PAD src0_sel:DWORD src1_sel:WORD_1
	s_waitcnt lgkmcnt(2)
	v_pk_add_f32 v[120:121], v[120:121], v[124:125]
	ds_bpermute_b32 v124, v173, v120
	s_waitcnt lgkmcnt(1)
	v_pk_add_f32 v[162:163], v[162:163], v[164:165]
	ds_bpermute_b32 v125, v173, v121
	ds_bpermute_b32 v164, v173, v162
	ds_bpermute_b32 v165, v173, v163
	v_add_u32_e32 v84, 0x10000, v84
	global_store_dwordx2 v84, v[174:175], s[96:97]
	s_and_saveexec_b64 s[8:9], vcc
	s_cbranch_execz .LBB0_86
	v_readlane_b32 s10, v253, 28
	v_lshlrev_b64 v[84:85], 5, v[128:129]
	v_readlane_b32 s11, v253, 29
	v_pk_add_f32 v[174:175], v[166:167], v[126:127]
	v_pk_add_f32 v[176:177], v[96:97], v[108:109]
	v_lshl_add_u64 v[84:85], s[10:11], 0, v[84:85]
	s_waitcnt lgkmcnt(2)
	v_pk_add_f32 v[124:125], v[120:121], v[124:125]
	s_waitcnt lgkmcnt(0)
	v_pk_add_f32 v[126:127], v[162:163], v[164:165]
	global_store_dwordx4 v[84:85], v[174:177], off
	global_store_dwordx4 v[84:85], v[124:127], off offset:16
	s_branch .LBB0_86

.LBB0_509:
	s_andn2_b64 vcc, exec, s[2:3]
	s_cbranch_vccnz .LBB0_503
	v_readlane_b32 s11, v255, 8
	v_readlane_b32 s12, v255, 6
	v_readlane_b32 s2, v253, 4
	v_readlane_b32 s3, v253, 5
	s_lshl_b32 s13, s11, 18
	s_add_u32 s2, s2, s13
	s_addc_u32 s3, s3, 0
	s_lshl_b32 s13, s12, 19
	s_add_u32 s4, s50, 0x5510000
	s_addc_u32 s5, s51, 0
	s_add_u32 s4, s4, s13
	s_addc_u32 s5, s5, 0
	v_and_b32_e32 v92, 63, v216
	v_lshrrev_b32_e32 v93, 6, v216
	v_lshrrev_b32_e32 v94, 2, v92
	v_and_b32_e32 v95, 3, v92
	v_readfirstlane_b32 s11, v93
	v_lshrrev_b32_e32 v100, 3, v94
	v_mul_u32_u24_e32 v100, 3, v100
	v_xor_b32_e32 v100, v95, v100
	v_lshlrev_b32_e32 v100, 4, v100
	v_lshl_add_u32 v101, v93, 5, v94
	v_lshlrev_b32_e32 v111, 4, v92
	v_lshl_add_u32 v203, v93, 11, v111
	v_add_u32_e32 v204, 0x400, v203
	v_lshl_add_u32 v101, v93, 6, v94
	v_lshlrev_b32_e32 v111, 4, v92
	v_lshl_add_u32 v205, v93, 12, v111
	v_add_u32_e32 v206, 0x400, v205
	v_add_u32_e32 v207, 0x800, v205
	v_add_u32_e32 v208, 0xc00, v205
	v_and_b32_e32 v102, 15, v92
	v_lshrrev_b32_e32 v103, 4, v92
	v_lshrrev_b32_e32 v108, 3, v102
	v_mul_u32_u24_e32 v108, 3, v108
	v_xor_b32_e32 v108, v103, v108
	v_lshlrev_b32_e32 v108, 4, v108
	v_lshl_add_u32 v108, v102, 6, v108
	v_lshrrev_b32_e32 v109, 1, v93
	v_and_b32_e32 v110, 1, v93
	v_lshl_add_u32 v209, v109, 12, v108
	v_lshl_add_u32 v210, v110, 13, v108
	s_lshl_b32 s12, s11, 12
	s_lshl_b32 s11, s11, 11
	s_barrier
	s_add_u32 m0, s11, 0x0
	s_nop 0
	global_load_lds_dwordx4 v203, s[2:3]
	s_add_u32 m0, s11, 0x400
	s_nop 0
	global_load_lds_dwordx4 v204, s[2:3]
	s_add_u32 m0, s12, 0x2000
	s_nop 0
	global_load_lds_dwordx4 v205, s[4:5]
	s_add_u32 m0, s12, 0x2400
	s_nop 0
	global_load_lds_dwordx4 v206, s[4:5]
	s_add_u32 m0, s12, 0x2800
	s_nop 0
	global_load_lds_dwordx4 v207, s[4:5]
	s_add_u32 m0, s12, 0x2c00
	s_nop 0
	global_load_lds_dwordx4 v208, s[4:5]
	s_add_u32 s2, s2, 0x2000
	s_addc_u32 s3, s3, 0
	s_add_u32 s4, s4, 0x4000
	s_addc_u32 s5, s5, 0
	s_add_u32 m0, s11, 0x6000
	s_nop 0
	global_load_lds_dwordx4 v203, s[2:3]
	s_add_u32 m0, s11, 0x6400
	s_nop 0
	global_load_lds_dwordx4 v204, s[2:3]
	s_add_u32 m0, s12, 0x8000
	s_nop 0
	global_load_lds_dwordx4 v205, s[4:5]
	s_add_u32 m0, s12, 0x8400
	s_nop 0
	global_load_lds_dwordx4 v206, s[4:5]
	s_add_u32 m0, s12, 0x8800
	s_nop 0
	global_load_lds_dwordx4 v207, s[4:5]
	s_add_u32 m0, s12, 0x8c00
	s_nop 0
	global_load_lds_dwordx4 v208, s[4:5]
	s_add_u32 s2, s2, 0x2000
	s_addc_u32 s3, s3, 0
	s_add_u32 s4, s4, 0x4000
	s_addc_u32 s5, s5, 0
	v_mov_b32_e32 v156, 0
	v_mov_b32_e32 v157, 0
	v_mov_b32_e32 v158, 0
	v_mov_b32_e32 v159, 0
	v_mov_b32_e32 v152, 0
	v_mov_b32_e32 v153, 0
	v_mov_b32_e32 v154, 0
	v_mov_b32_e32 v155, 0
	v_mov_b32_e32 v148, 0
	v_mov_b32_e32 v149, 0
	v_mov_b32_e32 v150, 0
	v_mov_b32_e32 v151, 0
	v_mov_b32_e32 v144, 0
	v_mov_b32_e32 v145, 0
	v_mov_b32_e32 v146, 0
	v_mov_b32_e32 v147, 0
	v_mov_b32_e32 v172, 0
	v_mov_b32_e32 v173, 0
	v_mov_b32_e32 v174, 0
	v_mov_b32_e32 v175, 0
	v_mov_b32_e32 v168, 0
	v_mov_b32_e32 v169, 0
	v_mov_b32_e32 v170, 0
	v_mov_b32_e32 v171, 0
	v_mov_b32_e32 v164, 0
	v_mov_b32_e32 v165, 0
	v_mov_b32_e32 v166, 0
	v_mov_b32_e32 v167, 0
	v_mov_b32_e32 v160, 0
	v_mov_b32_e32 v161, 0
	v_mov_b32_e32 v162, 0
	v_mov_b32_e32 v163, 0
	v_mov_b32_e32 v124, 0
	v_mov_b32_e32 v125, 0
	v_mov_b32_e32 v126, 0
	v_mov_b32_e32 v127, 0
	v_mov_b32_e32 v120, 0
	v_mov_b32_e32 v121, 0
	v_mov_b32_e32 v122, 0
	v_mov_b32_e32 v123, 0
	v_mov_b32_e32 v112, 0
	v_mov_b32_e32 v113, 0
	v_mov_b32_e32 v114, 0
	v_mov_b32_e32 v115, 0
	v_mov_b32_e32 v104, 0
	v_mov_b32_e32 v105, 0
	v_mov_b32_e32 v106, 0
	v_mov_b32_e32 v107, 0
	v_mov_b32_e32 v140, 0
	v_mov_b32_e32 v141, 0
	v_mov_b32_e32 v142, 0
	v_mov_b32_e32 v143, 0
	v_mov_b32_e32 v136, 0
	v_mov_b32_e32 v137, 0
	v_mov_b32_e32 v138, 0
	v_mov_b32_e32 v139, 0
	v_mov_b32_e32 v132, 0
	v_mov_b32_e32 v133, 0
	v_mov_b32_e32 v134, 0
	v_mov_b32_e32 v135, 0
	v_mov_b32_e32 v128, 0
	v_mov_b32_e32 v129, 0
	v_mov_b32_e32 v130, 0
	v_mov_b32_e32 v131, 0
	v_mov_b32_e32 v52, 0
	v_mov_b32_e32 v53, 0
	v_mov_b32_e32 v54, 0
	v_mov_b32_e32 v55, 0
	v_mov_b32_e32 v40, 0
	v_mov_b32_e32 v41, 0
	v_mov_b32_e32 v42, 0
	v_mov_b32_e32 v43, 0
	v_mov_b32_e32 v36, 0
	v_mov_b32_e32 v37, 0
	v_mov_b32_e32 v38, 0
	v_mov_b32_e32 v39, 0
	v_mov_b32_e32 v32, 0
	v_mov_b32_e32 v33, 0
	v_mov_b32_e32 v34, 0
	v_mov_b32_e32 v35, 0
	v_mov_b32_e32 v96, 0
	v_mov_b32_e32 v97, 0
	v_mov_b32_e32 v98, 0
	v_mov_b32_e32 v99, 0
	v_mov_b32_e32 v88, 0
	v_mov_b32_e32 v89, 0
	v_mov_b32_e32 v90, 0
	v_mov_b32_e32 v91, 0
	v_mov_b32_e32 v76, 0
	v_mov_b32_e32 v77, 0
	v_mov_b32_e32 v78, 0
	v_mov_b32_e32 v79, 0
	v_mov_b32_e32 v68, 0
	v_mov_b32_e32 v69, 0
	v_mov_b32_e32 v70, 0
	v_mov_b32_e32 v71, 0
	v_mov_b32_e32 v12, 0
	v_mov_b32_e32 v13, 0
	v_mov_b32_e32 v14, 0
	v_mov_b32_e32 v15, 0
	v_mov_b32_e32 v8, 0
	v_mov_b32_e32 v9, 0
	v_mov_b32_e32 v10, 0
	v_mov_b32_e32 v11, 0
	v_mov_b32_e32 v4, 0
	v_mov_b32_e32 v5, 0
	v_mov_b32_e32 v6, 0
	v_mov_b32_e32 v7, 0
	v_mov_b32_e32 v0, 0
	v_mov_b32_e32 v1, 0
	v_mov_b32_e32 v2, 0
	v_mov_b32_e32 v3, 0
	v_mov_b32_e32 v28, 0
	v_mov_b32_e32 v29, 0
	v_mov_b32_e32 v30, 0
	v_mov_b32_e32 v31, 0
	v_mov_b32_e32 v24, 0
	v_mov_b32_e32 v25, 0
	v_mov_b32_e32 v26, 0
	v_mov_b32_e32 v27, 0
	v_mov_b32_e32 v20, 0
	v_mov_b32_e32 v21, 0
	v_mov_b32_e32 v22, 0
	v_mov_b32_e32 v23, 0
	v_mov_b32_e32 v16, 0
	v_mov_b32_e32 v17, 0
	v_mov_b32_e32 v18, 0
	v_mov_b32_e32 v19, 0
	s_waitcnt vmcnt(6)
	s_barrier
	ds_read_b128 v[44:47], v209 offset:0
	ds_read_b128 v[48:51], v209 offset:1024
	ds_read_b128 v[56:59], v209 offset:2048
	ds_read_b128 v[60:63], v209 offset:3072
	ds_read_b128 v[92:95], v210 offset:8192
	ds_read_b128 v[100:103], v210 offset:9216
	ds_read_b128 v[108:111], v210 offset:10240
	ds_read_b128 v[116:119], v210 offset:11264
	ds_read_b128 v[176:179], v210 offset:12288
	ds_read_b128 v[180:183], v210 offset:13312
	s_add_u32 m0, s11, 0xc000
	s_nop 0
	global_load_lds_dwordx4 v203, s[2:3]
	s_add_u32 m0, s11, 0xc400
	s_nop 0
	global_load_lds_dwordx4 v204, s[2:3]
	s_add_u32 m0, s12, 0xe000
	s_nop 0
	global_load_lds_dwordx4 v205, s[4:5]
	s_add_u32 m0, s12, 0xe400
	s_nop 0
	global_load_lds_dwordx4 v206, s[4:5]
	s_add_u32 m0, s12, 0xe800
	s_nop 0
	global_load_lds_dwordx4 v207, s[4:5]
	s_add_u32 m0, s12, 0xec00
	s_nop 0
	global_load_lds_dwordx4 v208, s[4:5]
	s_add_u32 s2, s2, 0x2000
	s_addc_u32 s3, s3, 0
	s_add_u32 s4, s4, 0x4000
	s_addc_u32 s5, s5, 0
	ds_read_b128 v[184:187], v210 offset:14336
	ds_read_b128 v[188:191], v210 offset:15360
	s_waitcnt lgkmcnt(7)
	v_mfma_f32_16x16x32_bf16 v[156:159], v[92:95], v[44:47], v[156:159]
	v_mfma_f32_16x16x32_bf16 v[124:127], v[92:95], v[48:51], v[124:127]
	v_mfma_f32_16x16x32_bf16 v[52:55], v[92:95], v[56:59], v[52:55]
	v_mfma_f32_16x16x32_bf16 v[12:15], v[92:95], v[60:63], v[12:15]
	s_waitcnt lgkmcnt(6)
	v_mfma_f32_16x16x32_bf16 v[152:155], v[100:103], v[44:47], v[152:155]
	v_mfma_f32_16x16x32_bf16 v[120:123], v[100:103], v[48:51], v[120:123]
	v_mfma_f32_16x16x32_bf16 v[40:43], v[100:103], v[56:59], v[40:43]
	v_mfma_f32_16x16x32_bf16 v[8:11], v[100:103], v[60:63], v[8:11]
	s_waitcnt lgkmcnt(5)
	v_mfma_f32_16x16x32_bf16 v[148:151], v[108:111], v[44:47], v[148:151]
	v_mfma_f32_16x16x32_bf16 v[112:115], v[108:111], v[48:51], v[112:115]
	v_mfma_f32_16x16x32_bf16 v[36:39], v[108:111], v[56:59], v[36:39]
	v_mfma_f32_16x16x32_bf16 v[4:7], v[108:111], v[60:63], v[4:7]
	s_waitcnt lgkmcnt(4)
	v_mfma_f32_16x16x32_bf16 v[144:147], v[116:119], v[44:47], v[144:147]
	v_mfma_f32_16x16x32_bf16 v[104:107], v[116:119], v[48:51], v[104:107]
	v_mfma_f32_16x16x32_bf16 v[32:35], v[116:119], v[56:59], v[32:35]
	v_mfma_f32_16x16x32_bf16 v[0:3], v[116:119], v[60:63], v[0:3]
	s_waitcnt lgkmcnt(3)
	v_mfma_f32_16x16x32_bf16 v[172:175], v[176:179], v[44:47], v[172:175]
	v_mfma_f32_16x16x32_bf16 v[140:143], v[176:179], v[48:51], v[140:143]
	v_mfma_f32_16x16x32_bf16 v[96:99], v[176:179], v[56:59], v[96:99]
	v_mfma_f32_16x16x32_bf16 v[28:31], v[176:179], v[60:63], v[28:31]
	s_waitcnt lgkmcnt(2)
	v_mfma_f32_16x16x32_bf16 v[168:171], v[180:183], v[44:47], v[168:171]
	v_mfma_f32_16x16x32_bf16 v[136:139], v[180:183], v[48:51], v[136:139]
	v_mfma_f32_16x16x32_bf16 v[88:91], v[180:183], v[56:59], v[88:91]
	v_mfma_f32_16x16x32_bf16 v[24:27], v[180:183], v[60:63], v[24:27]
	s_waitcnt lgkmcnt(0)
	s_mov_b32 s13, 5
.Lg2_loop:
	s_waitcnt vmcnt(6)
	s_barrier
	ds_read_b128 v[64:67], v209 offset:24576
	ds_read_b128 v[72:75], v209 offset:25600
	ds_read_b128 v[80:83], v209 offset:26624
	ds_read_b128 v[84:87], v209 offset:27648
	ds_read_b128 v[92:95], v210 offset:32768
	ds_read_b128 v[100:103], v210 offset:33792
	ds_read_b128 v[108:111], v210 offset:34816
	ds_read_b128 v[116:119], v210 offset:35840
	ds_read_b128 v[176:179], v210 offset:36864
	ds_read_b128 v[180:183], v210 offset:37888
	v_mfma_f32_16x16x32_bf16 v[164:167], v[184:187], v[44:47], v[164:167]
	s_add_u32 m0, s11, 0x0
	v_mfma_f32_16x16x32_bf16 v[132:135], v[184:187], v[48:51], v[132:135]
	global_load_lds_dwordx4 v203, s[2:3]
	s_add_u32 m0, s11, 0x400
	v_mfma_f32_16x16x32_bf16 v[76:79], v[184:187], v[56:59], v[76:79]
	global_load_lds_dwordx4 v204, s[2:3]
	s_add_u32 m0, s12, 0x2000
	v_mfma_f32_16x16x32_bf16 v[20:23], v[184:187], v[60:63], v[20:23]
	global_load_lds_dwordx4 v205, s[4:5]
	s_add_u32 m0, s12, 0x2400
	v_mfma_f32_16x16x32_bf16 v[160:163], v[188:191], v[44:47], v[160:163]
	global_load_lds_dwordx4 v206, s[4:5]
	s_add_u32 m0, s12, 0x2800
	v_mfma_f32_16x16x32_bf16 v[128:131], v[188:191], v[48:51], v[128:131]
	global_load_lds_dwordx4 v207, s[4:5]
	s_add_u32 m0, s12, 0x2c00
	v_mfma_f32_16x16x32_bf16 v[68:71], v[188:191], v[56:59], v[68:71]
	global_load_lds_dwordx4 v208, s[4:5]
	v_mfma_f32_16x16x32_bf16 v[16:19], v[188:191], v[60:63], v[16:19]
	s_add_u32 s2, s2, 0x2000
	s_addc_u32 s3, s3, 0
	s_add_u32 s4, s4, 0x4000
	s_addc_u32 s5, s5, 0
	ds_read_b128 v[184:187], v210 offset:38912
	ds_read_b128 v[188:191], v210 offset:39936
	s_waitcnt lgkmcnt(7)
	v_mfma_f32_16x16x32_bf16 v[156:159], v[92:95], v[64:67], v[156:159]
	v_mfma_f32_16x16x32_bf16 v[124:127], v[92:95], v[72:75], v[124:127]
	v_mfma_f32_16x16x32_bf16 v[52:55], v[92:95], v[80:83], v[52:55]
	v_mfma_f32_16x16x32_bf16 v[12:15], v[92:95], v[84:87], v[12:15]
	s_waitcnt lgkmcnt(6)
	v_mfma_f32_16x16x32_bf16 v[152:155], v[100:103], v[64:67], v[152:155]
	v_mfma_f32_16x16x32_bf16 v[120:123], v[100:103], v[72:75], v[120:123]
	v_mfma_f32_16x16x32_bf16 v[40:43], v[100:103], v[80:83], v[40:43]
	v_mfma_f32_16x16x32_bf16 v[8:11], v[100:103], v[84:87], v[8:11]
	s_waitcnt lgkmcnt(5)
	v_mfma_f32_16x16x32_bf16 v[148:151], v[108:111], v[64:67], v[148:151]
	v_mfma_f32_16x16x32_bf16 v[112:115], v[108:111], v[72:75], v[112:115]
	v_mfma_f32_16x16x32_bf16 v[36:39], v[108:111], v[80:83], v[36:39]
	v_mfma_f32_16x16x32_bf16 v[4:7], v[108:111], v[84:87], v[4:7]
	s_waitcnt lgkmcnt(4)
	v_mfma_f32_16x16x32_bf16 v[144:147], v[116:119], v[64:67], v[144:147]
	v_mfma_f32_16x16x32_bf16 v[104:107], v[116:119], v[72:75], v[104:107]
	v_mfma_f32_16x16x32_bf16 v[32:35], v[116:119], v[80:83], v[32:35]
	v_mfma_f32_16x16x32_bf16 v[0:3], v[116:119], v[84:87], v[0:3]
	s_waitcnt lgkmcnt(3)
	v_mfma_f32_16x16x32_bf16 v[172:175], v[176:179], v[64:67], v[172:175]
	v_mfma_f32_16x16x32_bf16 v[140:143], v[176:179], v[72:75], v[140:143]
	v_mfma_f32_16x16x32_bf16 v[96:99], v[176:179], v[80:83], v[96:99]
	v_mfma_f32_16x16x32_bf16 v[28:31], v[176:179], v[84:87], v[28:31]
	s_waitcnt lgkmcnt(2)
	v_mfma_f32_16x16x32_bf16 v[168:171], v[180:183], v[64:67], v[168:171]
	v_mfma_f32_16x16x32_bf16 v[136:139], v[180:183], v[72:75], v[136:139]
	v_mfma_f32_16x16x32_bf16 v[88:91], v[180:183], v[80:83], v[88:91]
	v_mfma_f32_16x16x32_bf16 v[24:27], v[180:183], v[84:87], v[24:27]
	s_waitcnt lgkmcnt(0)
	s_waitcnt vmcnt(6)
	s_barrier
	ds_read_b128 v[44:47], v209 offset:49152
	ds_read_b128 v[48:51], v209 offset:50176
	ds_read_b128 v[56:59], v209 offset:51200
	ds_read_b128 v[60:63], v209 offset:52224
	ds_read_b128 v[92:95], v210 offset:57344
	ds_read_b128 v[100:103], v210 offset:58368
	ds_read_b128 v[108:111], v210 offset:59392
	ds_read_b128 v[116:119], v210 offset:60416
	ds_read_b128 v[176:179], v210 offset:61440
	ds_read_b128 v[180:183], v210 offset:62464
	v_mfma_f32_16x16x32_bf16 v[164:167], v[184:187], v[64:67], v[164:167]
	s_add_u32 m0, s11, 0x6000
	v_mfma_f32_16x16x32_bf16 v[132:135], v[184:187], v[72:75], v[132:135]
	global_load_lds_dwordx4 v203, s[2:3]
	s_add_u32 m0, s11, 0x6400
	v_mfma_f32_16x16x32_bf16 v[76:79], v[184:187], v[80:83], v[76:79]
	global_load_lds_dwordx4 v204, s[2:3]
	s_add_u32 m0, s12, 0x8000
	v_mfma_f32_16x16x32_bf16 v[20:23], v[184:187], v[84:87], v[20:23]
	global_load_lds_dwordx4 v205, s[4:5]
	s_add_u32 m0, s12, 0x8400
	v_mfma_f32_16x16x32_bf16 v[160:163], v[188:191], v[64:67], v[160:163]
	global_load_lds_dwordx4 v206, s[4:5]
	s_add_u32 m0, s12, 0x8800
	v_mfma_f32_16x16x32_bf16 v[128:131], v[188:191], v[72:75], v[128:131]
	global_load_lds_dwordx4 v207, s[4:5]
	s_add_u32 m0, s12, 0x8c00
	v_mfma_f32_16x16x32_bf16 v[68:71], v[188:191], v[80:83], v[68:71]
	global_load_lds_dwordx4 v208, s[4:5]
	v_mfma_f32_16x16x32_bf16 v[16:19], v[188:191], v[84:87], v[16:19]
	s_add_u32 s2, s2, 0x2000
	s_addc_u32 s3, s3, 0
	s_add_u32 s4, s4, 0x4000
	s_addc_u32 s5, s5, 0
	ds_read_b128 v[184:187], v210 offset:63488
	ds_read_b128 v[188:191], v210 offset:64512
	s_waitcnt lgkmcnt(7)
	v_mfma_f32_16x16x32_bf16 v[156:159], v[92:95], v[44:47], v[156:159]
	v_mfma_f32_16x16x32_bf16 v[124:127], v[92:95], v[48:51], v[124:127]
	v_mfma_f32_16x16x32_bf16 v[52:55], v[92:95], v[56:59], v[52:55]
	v_mfma_f32_16x16x32_bf16 v[12:15], v[92:95], v[60:63], v[12:15]
	s_waitcnt lgkmcnt(6)
	v_mfma_f32_16x16x32_bf16 v[152:155], v[100:103], v[44:47], v[152:155]
	v_mfma_f32_16x16x32_bf16 v[120:123], v[100:103], v[48:51], v[120:123]
	v_mfma_f32_16x16x32_bf16 v[40:43], v[100:103], v[56:59], v[40:43]
	v_mfma_f32_16x16x32_bf16 v[8:11], v[100:103], v[60:63], v[8:11]
	s_waitcnt lgkmcnt(5)
	v_mfma_f32_16x16x32_bf16 v[148:151], v[108:111], v[44:47], v[148:151]
	v_mfma_f32_16x16x32_bf16 v[112:115], v[108:111], v[48:51], v[112:115]
	v_mfma_f32_16x16x32_bf16 v[36:39], v[108:111], v[56:59], v[36:39]
	v_mfma_f32_16x16x32_bf16 v[4:7], v[108:111], v[60:63], v[4:7]
	s_waitcnt lgkmcnt(4)
	v_mfma_f32_16x16x32_bf16 v[144:147], v[116:119], v[44:47], v[144:147]
	v_mfma_f32_16x16x32_bf16 v[104:107], v[116:119], v[48:51], v[104:107]
	v_mfma_f32_16x16x32_bf16 v[32:35], v[116:119], v[56:59], v[32:35]
	v_mfma_f32_16x16x32_bf16 v[0:3], v[116:119], v[60:63], v[0:3]
	s_waitcnt lgkmcnt(3)
	v_mfma_f32_16x16x32_bf16 v[172:175], v[176:179], v[44:47], v[172:175]
	v_mfma_f32_16x16x32_bf16 v[140:143], v[176:179], v[48:51], v[140:143]
	v_mfma_f32_16x16x32_bf16 v[96:99], v[176:179], v[56:59], v[96:99]
	v_mfma_f32_16x16x32_bf16 v[28:31], v[176:179], v[60:63], v[28:31]
	s_waitcnt lgkmcnt(2)
	v_mfma_f32_16x16x32_bf16 v[168:171], v[180:183], v[44:47], v[168:171]
	v_mfma_f32_16x16x32_bf16 v[136:139], v[180:183], v[48:51], v[136:139]
	v_mfma_f32_16x16x32_bf16 v[88:91], v[180:183], v[56:59], v[88:91]
	v_mfma_f32_16x16x32_bf16 v[24:27], v[180:183], v[60:63], v[24:27]
	s_waitcnt lgkmcnt(0)
	s_waitcnt vmcnt(6)
	s_barrier
	ds_read_b128 v[64:67], v209 offset:0
	ds_read_b128 v[72:75], v209 offset:1024
	ds_read_b128 v[80:83], v209 offset:2048
	ds_read_b128 v[84:87], v209 offset:3072
	ds_read_b128 v[92:95], v210 offset:8192
	ds_read_b128 v[100:103], v210 offset:9216
	ds_read_b128 v[108:111], v210 offset:10240
	ds_read_b128 v[116:119], v210 offset:11264
	ds_read_b128 v[176:179], v210 offset:12288
	ds_read_b128 v[180:183], v210 offset:13312
	v_mfma_f32_16x16x32_bf16 v[164:167], v[184:187], v[44:47], v[164:167]
	s_add_u32 m0, s11, 0xc000
	v_mfma_f32_16x16x32_bf16 v[132:135], v[184:187], v[48:51], v[132:135]
	global_load_lds_dwordx4 v203, s[2:3]
	s_add_u32 m0, s11, 0xc400
	v_mfma_f32_16x16x32_bf16 v[76:79], v[184:187], v[56:59], v[76:79]
	global_load_lds_dwordx4 v204, s[2:3]
	s_add_u32 m0, s12, 0xe000
	v_mfma_f32_16x16x32_bf16 v[20:23], v[184:187], v[60:63], v[20:23]
	global_load_lds_dwordx4 v205, s[4:5]
	s_add_u32 m0, s12, 0xe400
	v_mfma_f32_16x16x32_bf16 v[160:163], v[188:191], v[44:47], v[160:163]
	global_load_lds_dwordx4 v206, s[4:5]
	s_add_u32 m0, s12, 0xe800
	v_mfma_f32_16x16x32_bf16 v[128:131], v[188:191], v[48:51], v[128:131]
	global_load_lds_dwordx4 v207, s[4:5]
	s_add_u32 m0, s12, 0xec00
	v_mfma_f32_16x16x32_bf16 v[68:71], v[188:191], v[56:59], v[68:71]
	global_load_lds_dwordx4 v208, s[4:5]
	v_mfma_f32_16x16x32_bf16 v[16:19], v[188:191], v[60:63], v[16:19]
	s_add_u32 s2, s2, 0x2000
	s_addc_u32 s3, s3, 0
	s_add_u32 s4, s4, 0x4000
	s_addc_u32 s5, s5, 0
	ds_read_b128 v[184:187], v210 offset:14336
	ds_read_b128 v[188:191], v210 offset:15360
	s_waitcnt lgkmcnt(7)
	v_mfma_f32_16x16x32_bf16 v[156:159], v[92:95], v[64:67], v[156:159]
	v_mfma_f32_16x16x32_bf16 v[124:127], v[92:95], v[72:75], v[124:127]
	v_mfma_f32_16x16x32_bf16 v[52:55], v[92:95], v[80:83], v[52:55]
	v_mfma_f32_16x16x32_bf16 v[12:15], v[92:95], v[84:87], v[12:15]
	s_waitcnt lgkmcnt(6)
	v_mfma_f32_16x16x32_bf16 v[152:155], v[100:103], v[64:67], v[152:155]
	v_mfma_f32_16x16x32_bf16 v[120:123], v[100:103], v[72:75], v[120:123]
	v_mfma_f32_16x16x32_bf16 v[40:43], v[100:103], v[80:83], v[40:43]
	v_mfma_f32_16x16x32_bf16 v[8:11], v[100:103], v[84:87], v[8:11]
	s_waitcnt lgkmcnt(5)
	v_mfma_f32_16x16x32_bf16 v[148:151], v[108:111], v[64:67], v[148:151]
	v_mfma_f32_16x16x32_bf16 v[112:115], v[108:111], v[72:75], v[112:115]
	v_mfma_f32_16x16x32_bf16 v[36:39], v[108:111], v[80:83], v[36:39]
	v_mfma_f32_16x16x32_bf16 v[4:7], v[108:111], v[84:87], v[4:7]
	s_waitcnt lgkmcnt(4)
	v_mfma_f32_16x16x32_bf16 v[144:147], v[116:119], v[64:67], v[144:147]
	v_mfma_f32_16x16x32_bf16 v[104:107], v[116:119], v[72:75], v[104:107]
	v_mfma_f32_16x16x32_bf16 v[32:35], v[116:119], v[80:83], v[32:35]
	v_mfma_f32_16x16x32_bf16 v[0:3], v[116:119], v[84:87], v[0:3]
	s_waitcnt lgkmcnt(3)
	v_mfma_f32_16x16x32_bf16 v[172:175], v[176:179], v[64:67], v[172:175]
	v_mfma_f32_16x16x32_bf16 v[140:143], v[176:179], v[72:75], v[140:143]
	v_mfma_f32_16x16x32_bf16 v[96:99], v[176:179], v[80:83], v[96:99]
	v_mfma_f32_16x16x32_bf16 v[28:31], v[176:179], v[84:87], v[28:31]
	s_waitcnt lgkmcnt(2)
	v_mfma_f32_16x16x32_bf16 v[168:171], v[180:183], v[64:67], v[168:171]
	v_mfma_f32_16x16x32_bf16 v[136:139], v[180:183], v[72:75], v[136:139]
	v_mfma_f32_16x16x32_bf16 v[88:91], v[180:183], v[80:83], v[88:91]
	v_mfma_f32_16x16x32_bf16 v[24:27], v[180:183], v[84:87], v[24:27]
	s_waitcnt lgkmcnt(0)
	s_waitcnt vmcnt(6)
	s_barrier
	ds_read_b128 v[44:47], v209 offset:24576
	ds_read_b128 v[48:51], v209 offset:25600
	ds_read_b128 v[56:59], v209 offset:26624
	ds_read_b128 v[60:63], v209 offset:27648
	ds_read_b128 v[92:95], v210 offset:32768
	ds_read_b128 v[100:103], v210 offset:33792
	ds_read_b128 v[108:111], v210 offset:34816
	ds_read_b128 v[116:119], v210 offset:35840
	ds_read_b128 v[176:179], v210 offset:36864
	ds_read_b128 v[180:183], v210 offset:37888
	v_mfma_f32_16x16x32_bf16 v[164:167], v[184:187], v[64:67], v[164:167]
	s_add_u32 m0, s11, 0x0
	v_mfma_f32_16x16x32_bf16 v[132:135], v[184:187], v[72:75], v[132:135]
	global_load_lds_dwordx4 v203, s[2:3]
	s_add_u32 m0, s11, 0x400
	v_mfma_f32_16x16x32_bf16 v[76:79], v[184:187], v[80:83], v[76:79]
	global_load_lds_dwordx4 v204, s[2:3]
	s_add_u32 m0, s12, 0x2000
	v_mfma_f32_16x16x32_bf16 v[20:23], v[184:187], v[84:87], v[20:23]
	global_load_lds_dwordx4 v205, s[4:5]
	s_add_u32 m0, s12, 0x2400
	v_mfma_f32_16x16x32_bf16 v[160:163], v[188:191], v[64:67], v[160:163]
	global_load_lds_dwordx4 v206, s[4:5]
	s_add_u32 m0, s12, 0x2800
	v_mfma_f32_16x16x32_bf16 v[128:131], v[188:191], v[72:75], v[128:131]
	global_load_lds_dwordx4 v207, s[4:5]
	s_add_u32 m0, s12, 0x2c00
	v_mfma_f32_16x16x32_bf16 v[68:71], v[188:191], v[80:83], v[68:71]
	global_load_lds_dwordx4 v208, s[4:5]
	v_mfma_f32_16x16x32_bf16 v[16:19], v[188:191], v[84:87], v[16:19]
	s_add_u32 s2, s2, 0x2000
	s_addc_u32 s3, s3, 0
	s_add_u32 s4, s4, 0x4000
	s_addc_u32 s5, s5, 0
	ds_read_b128 v[184:187], v210 offset:38912
	ds_read_b128 v[188:191], v210 offset:39936
	s_waitcnt lgkmcnt(7)
	v_mfma_f32_16x16x32_bf16 v[156:159], v[92:95], v[44:47], v[156:159]
	v_mfma_f32_16x16x32_bf16 v[124:127], v[92:95], v[48:51], v[124:127]
	v_mfma_f32_16x16x32_bf16 v[52:55], v[92:95], v[56:59], v[52:55]
	v_mfma_f32_16x16x32_bf16 v[12:15], v[92:95], v[60:63], v[12:15]
	s_waitcnt lgkmcnt(6)
	v_mfma_f32_16x16x32_bf16 v[152:155], v[100:103], v[44:47], v[152:155]
	v_mfma_f32_16x16x32_bf16 v[120:123], v[100:103], v[48:51], v[120:123]
	v_mfma_f32_16x16x32_bf16 v[40:43], v[100:103], v[56:59], v[40:43]
	v_mfma_f32_16x16x32_bf16 v[8:11], v[100:103], v[60:63], v[8:11]
	s_waitcnt lgkmcnt(5)
	v_mfma_f32_16x16x32_bf16 v[148:151], v[108:111], v[44:47], v[148:151]
	v_mfma_f32_16x16x32_bf16 v[112:115], v[108:111], v[48:51], v[112:115]
	v_mfma_f32_16x16x32_bf16 v[36:39], v[108:111], v[56:59], v[36:39]
	v_mfma_f32_16x16x32_bf16 v[4:7], v[108:111], v[60:63], v[4:7]
	s_waitcnt lgkmcnt(4)
	v_mfma_f32_16x16x32_bf16 v[144:147], v[116:119], v[44:47], v[144:147]
	v_mfma_f32_16x16x32_bf16 v[104:107], v[116:119], v[48:51], v[104:107]
	v_mfma_f32_16x16x32_bf16 v[32:35], v[116:119], v[56:59], v[32:35]
	v_mfma_f32_16x16x32_bf16 v[0:3], v[116:119], v[60:63], v[0:3]
	s_waitcnt lgkmcnt(3)
	v_mfma_f32_16x16x32_bf16 v[172:175], v[176:179], v[44:47], v[172:175]
	v_mfma_f32_16x16x32_bf16 v[140:143], v[176:179], v[48:51], v[140:143]
	v_mfma_f32_16x16x32_bf16 v[96:99], v[176:179], v[56:59], v[96:99]
	v_mfma_f32_16x16x32_bf16 v[28:31], v[176:179], v[60:63], v[28:31]
	s_waitcnt lgkmcnt(2)
	v_mfma_f32_16x16x32_bf16 v[168:171], v[180:183], v[44:47], v[168:171]
	v_mfma_f32_16x16x32_bf16 v[136:139], v[180:183], v[48:51], v[136:139]
	v_mfma_f32_16x16x32_bf16 v[88:91], v[180:183], v[56:59], v[88:91]
	v_mfma_f32_16x16x32_bf16 v[24:27], v[180:183], v[60:63], v[24:27]
	s_waitcnt lgkmcnt(0)
	s_waitcnt vmcnt(6)
	s_barrier
	ds_read_b128 v[64:67], v209 offset:49152
	ds_read_b128 v[72:75], v209 offset:50176
	ds_read_b128 v[80:83], v209 offset:51200
	ds_read_b128 v[84:87], v209 offset:52224
	ds_read_b128 v[92:95], v210 offset:57344
	ds_read_b128 v[100:103], v210 offset:58368
	ds_read_b128 v[108:111], v210 offset:59392
	ds_read_b128 v[116:119], v210 offset:60416
	ds_read_b128 v[176:179], v210 offset:61440
	ds_read_b128 v[180:183], v210 offset:62464
	v_mfma_f32_16x16x32_bf16 v[164:167], v[184:187], v[44:47], v[164:167]
	s_add_u32 m0, s11, 0x6000
	v_mfma_f32_16x16x32_bf16 v[132:135], v[184:187], v[48:51], v[132:135]
	global_load_lds_dwordx4 v203, s[2:3]
	s_add_u32 m0, s11, 0x6400
	v_mfma_f32_16x16x32_bf16 v[76:79], v[184:187], v[56:59], v[76:79]
	global_load_lds_dwordx4 v204, s[2:3]
	s_add_u32 m0, s12, 0x8000
	v_mfma_f32_16x16x32_bf16 v[20:23], v[184:187], v[60:63], v[20:23]
	global_load_lds_dwordx4 v205, s[4:5]
	s_add_u32 m0, s12, 0x8400
	v_mfma_f32_16x16x32_bf16 v[160:163], v[188:191], v[44:47], v[160:163]
	global_load_lds_dwordx4 v206, s[4:5]
	s_add_u32 m0, s12, 0x8800
	v_mfma_f32_16x16x32_bf16 v[128:131], v[188:191], v[48:51], v[128:131]
	global_load_lds_dwordx4 v207, s[4:5]
	s_add_u32 m0, s12, 0x8c00
	v_mfma_f32_16x16x32_bf16 v[68:71], v[188:191], v[56:59], v[68:71]
	global_load_lds_dwordx4 v208, s[4:5]
	v_mfma_f32_16x16x32_bf16 v[16:19], v[188:191], v[60:63], v[16:19]
	s_add_u32 s2, s2, 0x2000
	s_addc_u32 s3, s3, 0
	s_add_u32 s4, s4, 0x4000
	s_addc_u32 s5, s5, 0
	ds_read_b128 v[184:187], v210 offset:63488
	ds_read_b128 v[188:191], v210 offset:64512
	s_waitcnt lgkmcnt(7)
	v_mfma_f32_16x16x32_bf16 v[156:159], v[92:95], v[64:67], v[156:159]
	v_mfma_f32_16x16x32_bf16 v[124:127], v[92:95], v[72:75], v[124:127]
	v_mfma_f32_16x16x32_bf16 v[52:55], v[92:95], v[80:83], v[52:55]
	v_mfma_f32_16x16x32_bf16 v[12:15], v[92:95], v[84:87], v[12:15]
	s_waitcnt lgkmcnt(6)
	v_mfma_f32_16x16x32_bf16 v[152:155], v[100:103], v[64:67], v[152:155]
	v_mfma_f32_16x16x32_bf16 v[120:123], v[100:103], v[72:75], v[120:123]
	v_mfma_f32_16x16x32_bf16 v[40:43], v[100:103], v[80:83], v[40:43]
	v_mfma_f32_16x16x32_bf16 v[8:11], v[100:103], v[84:87], v[8:11]
	s_waitcnt lgkmcnt(5)
	v_mfma_f32_16x16x32_bf16 v[148:151], v[108:111], v[64:67], v[148:151]
	v_mfma_f32_16x16x32_bf16 v[112:115], v[108:111], v[72:75], v[112:115]
	v_mfma_f32_16x16x32_bf16 v[36:39], v[108:111], v[80:83], v[36:39]
	v_mfma_f32_16x16x32_bf16 v[4:7], v[108:111], v[84:87], v[4:7]
	s_waitcnt lgkmcnt(4)
	v_mfma_f32_16x16x32_bf16 v[144:147], v[116:119], v[64:67], v[144:147]
	v_mfma_f32_16x16x32_bf16 v[104:107], v[116:119], v[72:75], v[104:107]
	v_mfma_f32_16x16x32_bf16 v[32:35], v[116:119], v[80:83], v[32:35]
	v_mfma_f32_16x16x32_bf16 v[0:3], v[116:119], v[84:87], v[0:3]
	s_waitcnt lgkmcnt(3)
	v_mfma_f32_16x16x32_bf16 v[172:175], v[176:179], v[64:67], v[172:175]
	v_mfma_f32_16x16x32_bf16 v[140:143], v[176:179], v[72:75], v[140:143]
	v_mfma_f32_16x16x32_bf16 v[96:99], v[176:179], v[80:83], v[96:99]
	v_mfma_f32_16x16x32_bf16 v[28:31], v[176:179], v[84:87], v[28:31]
	s_waitcnt lgkmcnt(2)
	v_mfma_f32_16x16x32_bf16 v[168:171], v[180:183], v[64:67], v[168:171]
	v_mfma_f32_16x16x32_bf16 v[136:139], v[180:183], v[72:75], v[136:139]
	v_mfma_f32_16x16x32_bf16 v[88:91], v[180:183], v[80:83], v[88:91]
	v_mfma_f32_16x16x32_bf16 v[24:27], v[180:183], v[84:87], v[24:27]
	s_waitcnt lgkmcnt(0)
	s_waitcnt vmcnt(6)
	s_barrier
	ds_read_b128 v[44:47], v209 offset:0
	ds_read_b128 v[48:51], v209 offset:1024
	ds_read_b128 v[56:59], v209 offset:2048
	ds_read_b128 v[60:63], v209 offset:3072
	ds_read_b128 v[92:95], v210 offset:8192
	ds_read_b128 v[100:103], v210 offset:9216
	ds_read_b128 v[108:111], v210 offset:10240
	ds_read_b128 v[116:119], v210 offset:11264
	ds_read_b128 v[176:179], v210 offset:12288
	ds_read_b128 v[180:183], v210 offset:13312
	v_mfma_f32_16x16x32_bf16 v[164:167], v[184:187], v[64:67], v[164:167]
	s_add_u32 m0, s11, 0xc000
	v_mfma_f32_16x16x32_bf16 v[132:135], v[184:187], v[72:75], v[132:135]
	global_load_lds_dwordx4 v203, s[2:3]
	s_add_u32 m0, s11, 0xc400
	v_mfma_f32_16x16x32_bf16 v[76:79], v[184:187], v[80:83], v[76:79]
	global_load_lds_dwordx4 v204, s[2:3]
	s_add_u32 m0, s12, 0xe000
	v_mfma_f32_16x16x32_bf16 v[20:23], v[184:187], v[84:87], v[20:23]
	global_load_lds_dwordx4 v205, s[4:5]
	s_add_u32 m0, s12, 0xe400
	v_mfma_f32_16x16x32_bf16 v[160:163], v[188:191], v[64:67], v[160:163]
	global_load_lds_dwordx4 v206, s[4:5]
	s_add_u32 m0, s12, 0xe800
	v_mfma_f32_16x16x32_bf16 v[128:131], v[188:191], v[72:75], v[128:131]
	global_load_lds_dwordx4 v207, s[4:5]
	s_add_u32 m0, s12, 0xec00
	v_mfma_f32_16x16x32_bf16 v[68:71], v[188:191], v[80:83], v[68:71]
	global_load_lds_dwordx4 v208, s[4:5]
	v_mfma_f32_16x16x32_bf16 v[16:19], v[188:191], v[84:87], v[16:19]
	s_add_u32 s2, s2, 0x2000
	s_addc_u32 s3, s3, 0
	s_add_u32 s4, s4, 0x4000
	s_addc_u32 s5, s5, 0
	ds_read_b128 v[184:187], v210 offset:14336
	ds_read_b128 v[188:191], v210 offset:15360
	s_waitcnt lgkmcnt(7)
	v_mfma_f32_16x16x32_bf16 v[156:159], v[92:95], v[44:47], v[156:159]
	v_mfma_f32_16x16x32_bf16 v[124:127], v[92:95], v[48:51], v[124:127]
	v_mfma_f32_16x16x32_bf16 v[52:55], v[92:95], v[56:59], v[52:55]
	v_mfma_f32_16x16x32_bf16 v[12:15], v[92:95], v[60:63], v[12:15]
	s_waitcnt lgkmcnt(6)
	v_mfma_f32_16x16x32_bf16 v[152:155], v[100:103], v[44:47], v[152:155]
	v_mfma_f32_16x16x32_bf16 v[120:123], v[100:103], v[48:51], v[120:123]
	v_mfma_f32_16x16x32_bf16 v[40:43], v[100:103], v[56:59], v[40:43]
	v_mfma_f32_16x16x32_bf16 v[8:11], v[100:103], v[60:63], v[8:11]
	s_waitcnt lgkmcnt(5)
	v_mfma_f32_16x16x32_bf16 v[148:151], v[108:111], v[44:47], v[148:151]
	v_mfma_f32_16x16x32_bf16 v[112:115], v[108:111], v[48:51], v[112:115]
	v_mfma_f32_16x16x32_bf16 v[36:39], v[108:111], v[56:59], v[36:39]
	v_mfma_f32_16x16x32_bf16 v[4:7], v[108:111], v[60:63], v[4:7]
	s_waitcnt lgkmcnt(4)
	v_mfma_f32_16x16x32_bf16 v[144:147], v[116:119], v[44:47], v[144:147]
	v_mfma_f32_16x16x32_bf16 v[104:107], v[116:119], v[48:51], v[104:107]
	v_mfma_f32_16x16x32_bf16 v[32:35], v[116:119], v[56:59], v[32:35]
	v_mfma_f32_16x16x32_bf16 v[0:3], v[116:119], v[60:63], v[0:3]
	s_waitcnt lgkmcnt(3)
	v_mfma_f32_16x16x32_bf16 v[172:175], v[176:179], v[44:47], v[172:175]
	v_mfma_f32_16x16x32_bf16 v[140:143], v[176:179], v[48:51], v[140:143]
	v_mfma_f32_16x16x32_bf16 v[96:99], v[176:179], v[56:59], v[96:99]
	v_mfma_f32_16x16x32_bf16 v[28:31], v[176:179], v[60:63], v[28:31]
	s_waitcnt lgkmcnt(2)
	v_mfma_f32_16x16x32_bf16 v[168:171], v[180:183], v[44:47], v[168:171]
	v_mfma_f32_16x16x32_bf16 v[136:139], v[180:183], v[48:51], v[136:139]
	v_mfma_f32_16x16x32_bf16 v[88:91], v[180:183], v[56:59], v[88:91]
	v_mfma_f32_16x16x32_bf16 v[24:27], v[180:183], v[60:63], v[24:27]
	s_waitcnt lgkmcnt(0)
	s_sub_u32 s13, s13, 1
	s_cmp_lg_u32 s13, 0
	s_cbranch_scc1 .Lg2_loop
	s_waitcnt vmcnt(6)
	s_barrier
	ds_read_b128 v[64:67], v209 offset:24576
	ds_read_b128 v[72:75], v209 offset:25600
	ds_read_b128 v[80:83], v209 offset:26624
	ds_read_b128 v[84:87], v209 offset:27648
	ds_read_b128 v[92:95], v210 offset:32768
	ds_read_b128 v[100:103], v210 offset:33792
	ds_read_b128 v[108:111], v210 offset:34816
	ds_read_b128 v[116:119], v210 offset:35840
	ds_read_b128 v[176:179], v210 offset:36864
	ds_read_b128 v[180:183], v210 offset:37888
	v_mfma_f32_16x16x32_bf16 v[164:167], v[184:187], v[44:47], v[164:167]
	v_mfma_f32_16x16x32_bf16 v[132:135], v[184:187], v[48:51], v[132:135]
	v_mfma_f32_16x16x32_bf16 v[76:79], v[184:187], v[56:59], v[76:79]
	v_mfma_f32_16x16x32_bf16 v[20:23], v[184:187], v[60:63], v[20:23]
	v_mfma_f32_16x16x32_bf16 v[160:163], v[188:191], v[44:47], v[160:163]
	v_mfma_f32_16x16x32_bf16 v[128:131], v[188:191], v[48:51], v[128:131]
	v_mfma_f32_16x16x32_bf16 v[68:71], v[188:191], v[56:59], v[68:71]
	v_mfma_f32_16x16x32_bf16 v[16:19], v[188:191], v[60:63], v[16:19]
	ds_read_b128 v[184:187], v210 offset:38912
	ds_read_b128 v[188:191], v210 offset:39936
	s_waitcnt lgkmcnt(7)
	v_mfma_f32_16x16x32_bf16 v[156:159], v[92:95], v[64:67], v[156:159]
	v_mfma_f32_16x16x32_bf16 v[124:127], v[92:95], v[72:75], v[124:127]
	v_mfma_f32_16x16x32_bf16 v[52:55], v[92:95], v[80:83], v[52:55]
	v_mfma_f32_16x16x32_bf16 v[12:15], v[92:95], v[84:87], v[12:15]
	s_waitcnt lgkmcnt(6)
	v_mfma_f32_16x16x32_bf16 v[152:155], v[100:103], v[64:67], v[152:155]
	v_mfma_f32_16x16x32_bf16 v[120:123], v[100:103], v[72:75], v[120:123]
	v_mfma_f32_16x16x32_bf16 v[40:43], v[100:103], v[80:83], v[40:43]
	v_mfma_f32_16x16x32_bf16 v[8:11], v[100:103], v[84:87], v[8:11]
	s_waitcnt lgkmcnt(5)
	v_mfma_f32_16x16x32_bf16 v[148:151], v[108:111], v[64:67], v[148:151]
	v_mfma_f32_16x16x32_bf16 v[112:115], v[108:111], v[72:75], v[112:115]
	v_mfma_f32_16x16x32_bf16 v[36:39], v[108:111], v[80:83], v[36:39]
	v_mfma_f32_16x16x32_bf16 v[4:7], v[108:111], v[84:87], v[4:7]
	s_waitcnt lgkmcnt(4)
	v_mfma_f32_16x16x32_bf16 v[144:147], v[116:119], v[64:67], v[144:147]
	v_mfma_f32_16x16x32_bf16 v[104:107], v[116:119], v[72:75], v[104:107]
	v_mfma_f32_16x16x32_bf16 v[32:35], v[116:119], v[80:83], v[32:35]
	v_mfma_f32_16x16x32_bf16 v[0:3], v[116:119], v[84:87], v[0:3]
	s_waitcnt lgkmcnt(3)
	v_mfma_f32_16x16x32_bf16 v[172:175], v[176:179], v[64:67], v[172:175]
	v_mfma_f32_16x16x32_bf16 v[140:143], v[176:179], v[72:75], v[140:143]
	v_mfma_f32_16x16x32_bf16 v[96:99], v[176:179], v[80:83], v[96:99]
	v_mfma_f32_16x16x32_bf16 v[28:31], v[176:179], v[84:87], v[28:31]
	s_waitcnt lgkmcnt(2)
	v_mfma_f32_16x16x32_bf16 v[168:171], v[180:183], v[64:67], v[168:171]
	v_mfma_f32_16x16x32_bf16 v[136:139], v[180:183], v[72:75], v[136:139]
	v_mfma_f32_16x16x32_bf16 v[88:91], v[180:183], v[80:83], v[88:91]
	v_mfma_f32_16x16x32_bf16 v[24:27], v[180:183], v[84:87], v[24:27]
	s_waitcnt lgkmcnt(0)
	v_mfma_f32_16x16x32_bf16 v[164:167], v[184:187], v[64:67], v[164:167]
	v_mfma_f32_16x16x32_bf16 v[132:135], v[184:187], v[72:75], v[132:135]
	v_mfma_f32_16x16x32_bf16 v[76:79], v[184:187], v[80:83], v[76:79]
	v_mfma_f32_16x16x32_bf16 v[20:23], v[184:187], v[84:87], v[20:23]
	v_mfma_f32_16x16x32_bf16 v[160:163], v[188:191], v[64:67], v[160:163]
	v_mfma_f32_16x16x32_bf16 v[128:131], v[188:191], v[72:75], v[128:131]
	v_mfma_f32_16x16x32_bf16 v[68:71], v[188:191], v[80:83], v[68:71]
	v_mfma_f32_16x16x32_bf16 v[16:19], v[188:191], v[84:87], v[16:19]
	s_waitcnt vmcnt(0)
	s_nop 7
	s_nop 7
	s_branch .LBB0_502

.LBB0_874:
	s_andn2_b64 vcc, exec, s[2:3]
	s_cbranch_vccnz .LBB0_871
	v_readlane_b32 s20, v255, 4
	v_readlane_b32 s21, v255, 30
	v_and_b32_e32 v144, 63, v216
	v_lshrrev_b32_e32 v145, 6, v216
	v_lshrrev_b32_e32 v146, 3, v144
	v_and_b32_e32 v147, 7, v144
	v_readfirstlane_b32 s12, v145
	v_lshrrev_b32_e32 v148, 1, v146
	v_lshrrev_b32_e32 v149, 2, v146
	v_xor_b32_e32 v150, v148, v149
	v_xor_b32_e32 v151, 5, v150
	v_xor_b32_e32 v150, v147, v150
	v_xor_b32_e32 v151, v147, v151
	v_lshlrev_b32_e32 v150, 4, v150
	v_lshlrev_b32_e32 v151, 4, v151
	v_lshl_add_u32 v152, v145, 5, v146
	v_lshlrev_b32_e32 v153, 11, v152
	v_add_u32_e32 v192, v153, v150
	v_add_u32_e32 v193, v153, v151
	v_add_u32_e32 v193, 0x4000, v193
	v_add_u32_e32 v194, 0x8000, v192
	v_add_u32_e32 v195, 0x8000, v193
	v_lshlrev_b32_e32 v153, 6, v152
	v_lshrrev_b32_e32 v159, 6, v150
	v_lshlrev_b32_e32 v159, 13, v159
	v_and_b32_e32 v160, 0x30, v150
	v_add3_u32 v246, v153, v159, v160
	v_add_u32_e32 v248, 0x400, v246
	v_lshrrev_b32_e32 v159, 6, v151
	v_lshlrev_b32_e32 v159, 13, v159
	v_and_b32_e32 v160, 0x30, v151
	v_xor_b32_e32 v160, 0x30, v160
	v_add3_u32 v247, v153, v159, v160
	v_add_u32_e32 v247, 0x200, v247
	v_add_u32_e32 v249, 0x400, v247
	v_lshl_add_u32 v152, v145, 4, v146
	v_lshlrev_b32_e32 v153, 11, v152
	v_add_u32_e32 v196, v153, v150
	v_add_u32_e32 v197, v153, v151
	v_add_u32_e32 v197, 0x4000, v197
	v_lshlrev_b32_e32 v153, 9, v152
	v_add_u32_e32 v198, v153, v150
	v_add_u32_e32 v199, v153, v151
	v_add_u32_e32 v199, 0x1000, v199
	v_and_b32_e32 v154, 15, v144
	v_lshrrev_b32_e32 v155, 4, v144
	v_lshrrev_b32_e32 v156, 1, v154
	v_lshrrev_b32_e32 v157, 2, v154
	v_lshrrev_b32_e32 v158, 3, v154
	v_xor_b32_e32 v157, v157, v158
	v_and_b32_e32 v157, 1, v157
	v_xor_b32_e32 v156, v156, v157
	v_xor_b32_e32 v156, v155, v156
	v_lshlrev_b32_e32 v156, 4, v156
	v_lshl_add_u32 v156, v154, 7, v156
	v_lshrrev_b32_e32 v157, 1, v145
	v_and_b32_e32 v158, 1, v145
	v_lshl_add_u32 v203, v157, 13, v156
	v_xor_b32_e32 v204, 64, v203
	v_lshl_add_u32 v205, v158, 12, v156
	v_xor_b32_e32 v206, 64, v205
	s_lshl_b32 s13, s12, 11
	s_lshl_b32 s12, s12, 12
	s_mov_b32 s30, 0xffff0000
	v_readlane_b32 s2, v253, 4
	v_readlane_b32 s3, v253, 5
	s_lshl_b32 s14, s20, 18
	s_add_u32 s2, s2, s14
	s_addc_u32 s3, s3, 0
	s_add_u32 s8, s50, 0xe629000
	s_addc_u32 s9, s51, 0
	s_add_u32 s8, s8, s14
	s_addc_u32 s9, s9, 0
	s_lshl_b32 s14, s21, 17
	s_add_u32 s4, s50, 0x5990000
	s_addc_u32 s5, s51, 0
	s_add_u32 s4, s4, s14
	s_addc_u32 s5, s5, 0
	s_lshl_b32 s14, s21, 15
	s_add_u32 s10, s50, 0x6190000
	s_addc_u32 s11, s51, 0
	s_add_u32 s10, s10, s14
	s_addc_u32 s11, s11, 0
	s_add_u32 m0, s12, 0x0
	s_nop 0
	global_load_lds_dwordx4 v246, s[2:3]
	s_add_u32 m0, s12, 0x400
	s_nop 0
	global_load_lds_dwordx4 v247, s[2:3]
	s_add_u32 m0, s12, 0x800
	s_nop 0
	global_load_lds_dwordx4 v248, s[2:3]
	s_add_u32 m0, s12, 0xc00
	s_nop 0
	global_load_lds_dwordx4 v249, s[2:3]
	s_add_u32 m0, s13, 0x4000
	s_nop 0
	global_load_lds_dwordx4 v196, s[4:5]
	s_add_u32 m0, s13, 0x4400
	s_nop 0
	global_load_lds_dwordx4 v197, s[4:5]
	s_add_u32 s2, s2, 0x4000
	s_addc_u32 s3, s3, 0
	s_add_u32 s4, s4, 0x80
	s_addc_u32 s5, s5, 0
	v_mov_b32_e32 v0, 0
	v_mov_b32_e32 v1, 0
	v_mov_b32_e32 v2, 0
	v_mov_b32_e32 v3, 0
	v_mov_b32_e32 v4, 0
	v_mov_b32_e32 v5, 0
	v_mov_b32_e32 v6, 0
	v_mov_b32_e32 v7, 0
	v_mov_b32_e32 v8, 0
	v_mov_b32_e32 v9, 0
	v_mov_b32_e32 v10, 0
	v_mov_b32_e32 v11, 0
	v_mov_b32_e32 v12, 0
	v_mov_b32_e32 v13, 0
	v_mov_b32_e32 v14, 0
	v_mov_b32_e32 v15, 0
	v_mov_b32_e32 v16, 0
	v_mov_b32_e32 v17, 0
	v_mov_b32_e32 v18, 0
	v_mov_b32_e32 v19, 0
	v_mov_b32_e32 v20, 0
	v_mov_b32_e32 v21, 0
	v_mov_b32_e32 v22, 0
	v_mov_b32_e32 v23, 0
	v_mov_b32_e32 v24, 0
	v_mov_b32_e32 v25, 0
	v_mov_b32_e32 v26, 0
	v_mov_b32_e32 v27, 0
	v_mov_b32_e32 v28, 0
	v_mov_b32_e32 v29, 0
	v_mov_b32_e32 v30, 0
	v_mov_b32_e32 v31, 0
	v_mov_b32_e32 v32, 0
	v_mov_b32_e32 v33, 0
	v_mov_b32_e32 v34, 0
	v_mov_b32_e32 v35, 0
	v_mov_b32_e32 v36, 0
	v_mov_b32_e32 v37, 0
	v_mov_b32_e32 v38, 0
	v_mov_b32_e32 v39, 0
	v_mov_b32_e32 v40, 0
	v_mov_b32_e32 v41, 0
	v_mov_b32_e32 v42, 0
	v_mov_b32_e32 v43, 0
	v_mov_b32_e32 v44, 0
	v_mov_b32_e32 v45, 0
	v_mov_b32_e32 v46, 0
	v_mov_b32_e32 v47, 0
	v_mov_b32_e32 v48, 0
	v_mov_b32_e32 v49, 0
	v_mov_b32_e32 v50, 0
	v_mov_b32_e32 v51, 0
	v_mov_b32_e32 v52, 0
	v_mov_b32_e32 v53, 0
	v_mov_b32_e32 v54, 0
	v_mov_b32_e32 v55, 0
	v_mov_b32_e32 v56, 0
	v_mov_b32_e32 v57, 0
	v_mov_b32_e32 v58, 0
	v_mov_b32_e32 v59, 0
	v_mov_b32_e32 v60, 0
	v_mov_b32_e32 v61, 0
	v_mov_b32_e32 v62, 0
	v_mov_b32_e32 v63, 0
	s_waitcnt vmcnt(0)
	s_barrier
	s_add_u32 m0, s12, 0x6000
	ds_read_b128 v[96:99], v203 offset:0
	global_load_lds_dwordx4 v246, s[2:3]
	s_add_u32 m0, s12, 0x6400
	ds_read_b128 v[100:103], v203 offset:2048
	global_load_lds_dwordx4 v247, s[2:3]
	s_add_u32 m0, s12, 0x6800
	ds_read_b128 v[104:107], v203 offset:4096
	global_load_lds_dwordx4 v248, s[2:3]
	s_add_u32 m0, s12, 0x6c00
	ds_read_b128 v[108:111], v203 offset:6144
	global_load_lds_dwordx4 v249, s[2:3]
	s_add_u32 m0, s13, 0xa000
	ds_read_b128 v[128:131], v205 offset:16384
	global_load_lds_dwordx4 v196, s[4:5]
	s_add_u32 m0, s13, 0xa400
	ds_read_b128 v[132:135], v205 offset:18432
	global_load_lds_dwordx4 v197, s[4:5]
	s_add_u32 s2, s2, 0x4000
	s_addc_u32 s3, s3, 0
	s_add_u32 s4, s4, 0x80
	s_addc_u32 s5, s5, 0
	ds_read_b128 v[112:115], v204 offset:0
	ds_read_b128 v[116:119], v204 offset:2048
	ds_read_b128 v[120:123], v204 offset:4096
	ds_read_b128 v[124:127], v204 offset:6144
	ds_read_b128 v[136:139], v206 offset:16384
	ds_read_b128 v[140:143], v206 offset:18432
	s_waitcnt lgkmcnt(0)
	s_mov_b32 s17, 0
.Lg4_nloop:
	s_waitcnt vmcnt(0)
	s_barrier
	v_mfma_f32_16x16x32_bf16 v[32:35], v[128:131], v[96:99], v[32:35]
	s_add_u32 m0, s12, 0x0
	ds_read_b128 v[144:147], v203 offset:24576
	v_mfma_f32_16x16x32_bf16 v[36:39], v[132:135], v[96:99], v[36:39]
	global_load_lds_dwordx4 v246, s[2:3]
	s_add_u32 m0, s12, 0x400
	ds_read_b128 v[148:151], v203 offset:26624
	v_mfma_f32_16x16x32_bf16 v[40:43], v[128:131], v[100:103], v[40:43]
	global_load_lds_dwordx4 v247, s[2:3]
	s_add_u32 m0, s12, 0x800
	ds_read_b128 v[152:155], v203 offset:28672
	v_mfma_f32_16x16x32_bf16 v[44:47], v[132:135], v[100:103], v[44:47]
	global_load_lds_dwordx4 v248, s[2:3]
	s_add_u32 m0, s12, 0xc00
	ds_read_b128 v[156:159], v203 offset:30720
	v_mfma_f32_16x16x32_bf16 v[48:51], v[128:131], v[104:107], v[48:51]
	global_load_lds_dwordx4 v249, s[2:3]
	s_add_u32 m0, s13, 0x4000
	ds_read_b128 v[176:179], v205 offset:40960
	v_mfma_f32_16x16x32_bf16 v[52:55], v[132:135], v[104:107], v[52:55]
	global_load_lds_dwordx4 v196, s[4:5]
	s_add_u32 m0, s13, 0x4400
	ds_read_b128 v[180:183], v205 offset:43008
	v_mfma_f32_16x16x32_bf16 v[56:59], v[128:131], v[108:111], v[56:59]
	global_load_lds_dwordx4 v197, s[4:5]
	ds_read_b128 v[160:163], v204 offset:24576
	v_mfma_f32_16x16x32_bf16 v[60:63], v[132:135], v[108:111], v[60:63]
	s_add_u32 s2, s2, 0x4000
	s_addc_u32 s3, s3, 0
	ds_read_b128 v[164:167], v204 offset:26624
	v_mfma_f32_16x16x32_bf16 v[32:35], v[136:139], v[112:115], v[32:35]
	s_add_u32 s4, s4, 0x80
	s_addc_u32 s5, s5, 0
	ds_read_b128 v[168:171], v204 offset:28672
	v_mfma_f32_16x16x32_bf16 v[36:39], v[140:143], v[112:115], v[36:39]
	ds_read_b128 v[172:175], v204 offset:30720
	v_mfma_f32_16x16x32_bf16 v[40:43], v[136:139], v[116:119], v[40:43]
	ds_read_b128 v[184:187], v206 offset:40960
	v_mfma_f32_16x16x32_bf16 v[44:47], v[140:143], v[116:119], v[44:47]
	ds_read_b128 v[188:191], v206 offset:43008
	v_mfma_f32_16x16x32_bf16 v[48:51], v[136:139], v[120:123], v[48:51]
	v_mfma_f32_16x16x32_bf16 v[52:55], v[140:143], v[120:123], v[52:55]
	v_mfma_f32_16x16x32_bf16 v[56:59], v[136:139], v[124:127], v[56:59]
	v_mfma_f32_16x16x32_bf16 v[60:63], v[140:143], v[124:127], v[60:63]
	s_waitcnt lgkmcnt(0)
	s_waitcnt vmcnt(0)
	s_barrier
	v_mfma_f32_16x16x32_bf16 v[32:35], v[176:179], v[144:147], v[32:35]
	s_add_u32 m0, s12, 0x6000
	ds_read_b128 v[96:99], v203 offset:0
	v_mfma_f32_16x16x32_bf16 v[36:39], v[180:183], v[144:147], v[36:39]
	global_load_lds_dwordx4 v246, s[2:3]
	s_add_u32 m0, s12, 0x6400
	ds_read_b128 v[100:103], v203 offset:2048
	v_mfma_f32_16x16x32_bf16 v[40:43], v[176:179], v[148:151], v[40:43]
	global_load_lds_dwordx4 v247, s[2:3]
	s_add_u32 m0, s12, 0x6800
	ds_read_b128 v[104:107], v203 offset:4096
	v_mfma_f32_16x16x32_bf16 v[44:47], v[180:183], v[148:151], v[44:47]
	global_load_lds_dwordx4 v248, s[2:3]
	s_add_u32 m0, s12, 0x6c00
	ds_read_b128 v[108:111], v203 offset:6144
	v_mfma_f32_16x16x32_bf16 v[48:51], v[176:179], v[152:155], v[48:51]
	global_load_lds_dwordx4 v249, s[2:3]
	s_add_u32 m0, s13, 0xa000
	ds_read_b128 v[128:131], v205 offset:16384
	v_mfma_f32_16x16x32_bf16 v[52:55], v[180:183], v[152:155], v[52:55]
	global_load_lds_dwordx4 v196, s[4:5]
	s_add_u32 m0, s13, 0xa400
	ds_read_b128 v[132:135], v205 offset:18432
	v_mfma_f32_16x16x32_bf16 v[56:59], v[176:179], v[156:159], v[56:59]
	global_load_lds_dwordx4 v197, s[4:5]
	ds_read_b128 v[112:115], v204 offset:0
	v_mfma_f32_16x16x32_bf16 v[60:63], v[180:183], v[156:159], v[60:63]
	s_add_u32 s2, s2, 0x4000
	s_addc_u32 s3, s3, 0
	ds_read_b128 v[116:119], v204 offset:2048
	v_mfma_f32_16x16x32_bf16 v[32:35], v[184:187], v[160:163], v[32:35]
	s_add_u32 s4, s4, 0x80
	s_addc_u32 s5, s5, 0
	ds_read_b128 v[120:123], v204 offset:4096
	v_mfma_f32_16x16x32_bf16 v[36:39], v[188:191], v[160:163], v[36:39]
	ds_read_b128 v[124:127], v204 offset:6144
	v_mfma_f32_16x16x32_bf16 v[40:43], v[184:187], v[164:167], v[40:43]
	ds_read_b128 v[136:139], v206 offset:16384
	v_mfma_f32_16x16x32_bf16 v[44:47], v[188:191], v[164:167], v[44:47]
	ds_read_b128 v[140:143], v206 offset:18432
	v_mfma_f32_16x16x32_bf16 v[48:51], v[184:187], v[168:171], v[48:51]
	v_mfma_f32_16x16x32_bf16 v[52:55], v[188:191], v[168:171], v[52:55]
	v_mfma_f32_16x16x32_bf16 v[56:59], v[184:187], v[172:175], v[56:59]
	v_mfma_f32_16x16x32_bf16 v[60:63], v[188:191], v[172:175], v[60:63]
	s_waitcnt lgkmcnt(0)
	s_waitcnt vmcnt(0)
	s_barrier
	v_mfma_f32_16x16x32_bf16 v[32:35], v[128:131], v[96:99], v[32:35]
	s_add_u32 m0, s12, 0x0
	ds_read_b128 v[144:147], v203 offset:24576
	v_mfma_f32_16x16x32_bf16 v[36:39], v[132:135], v[96:99], v[36:39]
	global_load_lds_dwordx4 v246, s[2:3]
	s_add_u32 m0, s12, 0x400
	ds_read_b128 v[148:151], v203 offset:26624
	v_mfma_f32_16x16x32_bf16 v[40:43], v[128:131], v[100:103], v[40:43]
	global_load_lds_dwordx4 v247, s[2:3]
	s_add_u32 m0, s12, 0x800
	ds_read_b128 v[152:155], v203 offset:28672
	v_mfma_f32_16x16x32_bf16 v[44:47], v[132:135], v[100:103], v[44:47]
	global_load_lds_dwordx4 v248, s[2:3]
	s_add_u32 m0, s12, 0xc00
	ds_read_b128 v[156:159], v203 offset:30720
	v_mfma_f32_16x16x32_bf16 v[48:51], v[128:131], v[104:107], v[48:51]
	global_load_lds_dwordx4 v249, s[2:3]
	s_add_u32 m0, s13, 0x4000
	ds_read_b128 v[176:179], v205 offset:40960
	v_mfma_f32_16x16x32_bf16 v[52:55], v[132:135], v[104:107], v[52:55]
	global_load_lds_dwordx4 v196, s[4:5]
	s_add_u32 m0, s13, 0x4400
	ds_read_b128 v[180:183], v205 offset:43008
	v_mfma_f32_16x16x32_bf16 v[56:59], v[128:131], v[108:111], v[56:59]
	global_load_lds_dwordx4 v197, s[4:5]
	ds_read_b128 v[160:163], v204 offset:24576
	v_mfma_f32_16x16x32_bf16 v[60:63], v[132:135], v[108:111], v[60:63]
	s_add_u32 s2, s2, 0x4000
	s_addc_u32 s3, s3, 0
	ds_read_b128 v[164:167], v204 offset:26624
	v_mfma_f32_16x16x32_bf16 v[32:35], v[136:139], v[112:115], v[32:35]
	s_add_u32 s4, s4, 0x80
	s_addc_u32 s5, s5, 0
	ds_read_b128 v[168:171], v204 offset:28672
	v_mfma_f32_16x16x32_bf16 v[36:39], v[140:143], v[112:115], v[36:39]
	ds_read_b128 v[172:175], v204 offset:30720
	v_mfma_f32_16x16x32_bf16 v[40:43], v[136:139], v[116:119], v[40:43]
	ds_read_b128 v[184:187], v206 offset:40960
	v_mfma_f32_16x16x32_bf16 v[44:47], v[140:143], v[116:119], v[44:47]
	ds_read_b128 v[188:191], v206 offset:43008
	v_mfma_f32_16x16x32_bf16 v[48:51], v[136:139], v[120:123], v[48:51]
	v_mfma_f32_16x16x32_bf16 v[52:55], v[140:143], v[120:123], v[52:55]
	v_mfma_f32_16x16x32_bf16 v[56:59], v[136:139], v[124:127], v[56:59]
	v_mfma_f32_16x16x32_bf16 v[60:63], v[140:143], v[124:127], v[60:63]
	s_waitcnt lgkmcnt(0)
	s_waitcnt vmcnt(0)
	s_barrier
	v_mfma_f32_16x16x32_bf16 v[32:35], v[176:179], v[144:147], v[32:35]
	s_add_u32 m0, s12, 0x6000
	ds_read_b128 v[96:99], v203 offset:0
	v_mfma_f32_16x16x32_bf16 v[36:39], v[180:183], v[144:147], v[36:39]
	global_load_lds_dwordx4 v246, s[2:3]
	s_add_u32 m0, s12, 0x6400
	ds_read_b128 v[100:103], v203 offset:2048
	v_mfma_f32_16x16x32_bf16 v[40:43], v[176:179], v[148:151], v[40:43]
	global_load_lds_dwordx4 v247, s[2:3]
	s_add_u32 m0, s12, 0x6800
	ds_read_b128 v[104:107], v203 offset:4096
	v_mfma_f32_16x16x32_bf16 v[44:47], v[180:183], v[148:151], v[44:47]
	global_load_lds_dwordx4 v248, s[2:3]
	s_add_u32 m0, s12, 0x6c00
	ds_read_b128 v[108:111], v203 offset:6144
	v_mfma_f32_16x16x32_bf16 v[48:51], v[176:179], v[152:155], v[48:51]
	global_load_lds_dwordx4 v249, s[2:3]
	s_add_u32 m0, s13, 0xa000
	ds_read_b128 v[128:131], v205 offset:16384
	v_mfma_f32_16x16x32_bf16 v[52:55], v[180:183], v[152:155], v[52:55]
	global_load_lds_dwordx4 v196, s[4:5]
	s_add_u32 m0, s13, 0xa400
	ds_read_b128 v[132:135], v205 offset:18432
	v_mfma_f32_16x16x32_bf16 v[56:59], v[176:179], v[156:159], v[56:59]
	global_load_lds_dwordx4 v197, s[4:5]
	ds_read_b128 v[112:115], v204 offset:0
	v_mfma_f32_16x16x32_bf16 v[60:63], v[180:183], v[156:159], v[60:63]
	s_add_u32 s2, s2, 0x4000
	s_addc_u32 s3, s3, 0
	ds_read_b128 v[116:119], v204 offset:2048
	v_mfma_f32_16x16x32_bf16 v[32:35], v[184:187], v[160:163], v[32:35]
	s_add_u32 s4, s4, 0x80
	s_addc_u32 s5, s5, 0
	ds_read_b128 v[120:123], v204 offset:4096
	v_mfma_f32_16x16x32_bf16 v[36:39], v[188:191], v[160:163], v[36:39]
	ds_read_b128 v[124:127], v204 offset:6144
	v_mfma_f32_16x16x32_bf16 v[40:43], v[184:187], v[164:167], v[40:43]
	ds_read_b128 v[136:139], v206 offset:16384
	v_mfma_f32_16x16x32_bf16 v[44:47], v[188:191], v[164:167], v[44:47]
	ds_read_b128 v[140:143], v206 offset:18432
	v_mfma_f32_16x16x32_bf16 v[48:51], v[184:187], v[168:171], v[48:51]
	v_mfma_f32_16x16x32_bf16 v[52:55], v[188:191], v[168:171], v[52:55]
	v_mfma_f32_16x16x32_bf16 v[56:59], v[184:187], v[172:175], v[56:59]
	v_mfma_f32_16x16x32_bf16 v[60:63], v[188:191], v[172:175], v[60:63]
	s_waitcnt lgkmcnt(0)
	s_waitcnt vmcnt(0)
	s_barrier
	v_mfma_f32_16x16x32_bf16 v[32:35], v[128:131], v[96:99], v[32:35]
	s_add_u32 m0, s12, 0x0
	ds_read_b128 v[144:147], v203 offset:24576
	v_mfma_f32_16x16x32_bf16 v[36:39], v[132:135], v[96:99], v[36:39]
	global_load_lds_dwordx4 v246, s[2:3]
	s_add_u32 m0, s12, 0x400
	ds_read_b128 v[148:151], v203 offset:26624
	v_mfma_f32_16x16x32_bf16 v[40:43], v[128:131], v[100:103], v[40:43]
	global_load_lds_dwordx4 v247, s[2:3]
	s_add_u32 m0, s12, 0x800
	ds_read_b128 v[152:155], v203 offset:28672
	v_mfma_f32_16x16x32_bf16 v[44:47], v[132:135], v[100:103], v[44:47]
	global_load_lds_dwordx4 v248, s[2:3]
	s_add_u32 m0, s12, 0xc00
	ds_read_b128 v[156:159], v203 offset:30720
	v_mfma_f32_16x16x32_bf16 v[48:51], v[128:131], v[104:107], v[48:51]
	global_load_lds_dwordx4 v249, s[2:3]
	s_add_u32 m0, s13, 0x4000
	ds_read_b128 v[176:179], v205 offset:40960
	v_mfma_f32_16x16x32_bf16 v[52:55], v[132:135], v[104:107], v[52:55]
	global_load_lds_dwordx4 v196, s[4:5]
	s_add_u32 m0, s13, 0x4400
	ds_read_b128 v[180:183], v205 offset:43008
	v_mfma_f32_16x16x32_bf16 v[56:59], v[128:131], v[108:111], v[56:59]
	global_load_lds_dwordx4 v197, s[4:5]
	ds_read_b128 v[160:163], v204 offset:24576
	v_mfma_f32_16x16x32_bf16 v[60:63], v[132:135], v[108:111], v[60:63]
	s_add_u32 s2, s2, 0x4000
	s_addc_u32 s3, s3, 0
	ds_read_b128 v[164:167], v204 offset:26624
	v_mfma_f32_16x16x32_bf16 v[32:35], v[136:139], v[112:115], v[32:35]
	s_add_u32 s4, s4, 0x80
	s_addc_u32 s5, s5, 0
	ds_read_b128 v[168:171], v204 offset:28672
	v_mfma_f32_16x16x32_bf16 v[36:39], v[140:143], v[112:115], v[36:39]
	ds_read_b128 v[172:175], v204 offset:30720
	v_mfma_f32_16x16x32_bf16 v[40:43], v[136:139], v[116:119], v[40:43]
	ds_read_b128 v[184:187], v206 offset:40960
	v_mfma_f32_16x16x32_bf16 v[44:47], v[140:143], v[116:119], v[44:47]
	ds_read_b128 v[188:191], v206 offset:43008
	v_mfma_f32_16x16x32_bf16 v[48:51], v[136:139], v[120:123], v[48:51]
	v_mfma_f32_16x16x32_bf16 v[52:55], v[140:143], v[120:123], v[52:55]
	v_mfma_f32_16x16x32_bf16 v[56:59], v[136:139], v[124:127], v[56:59]
	v_mfma_f32_16x16x32_bf16 v[60:63], v[140:143], v[124:127], v[60:63]
	s_waitcnt lgkmcnt(0)
	s_waitcnt vmcnt(0)
	s_barrier
	v_mfma_f32_16x16x32_bf16 v[32:35], v[176:179], v[144:147], v[32:35]
	s_add_u32 m0, s12, 0x6000
	ds_read_b128 v[96:99], v203 offset:0
	v_mfma_f32_16x16x32_bf16 v[36:39], v[180:183], v[144:147], v[36:39]
	global_load_lds_dwordx4 v246, s[2:3]
	s_add_u32 m0, s12, 0x6400
	ds_read_b128 v[100:103], v203 offset:2048
	v_mfma_f32_16x16x32_bf16 v[40:43], v[176:179], v[148:151], v[40:43]
	global_load_lds_dwordx4 v247, s[2:3]
	s_add_u32 m0, s12, 0x6800
	ds_read_b128 v[104:107], v203 offset:4096
	v_mfma_f32_16x16x32_bf16 v[44:47], v[180:183], v[148:151], v[44:47]
	global_load_lds_dwordx4 v248, s[2:3]
	s_add_u32 m0, s12, 0x6c00
	ds_read_b128 v[108:111], v203 offset:6144
	v_mfma_f32_16x16x32_bf16 v[48:51], v[176:179], v[152:155], v[48:51]
	global_load_lds_dwordx4 v249, s[2:3]
	s_add_u32 m0, s13, 0xa000
	ds_read_b128 v[128:131], v205 offset:16384
	v_mfma_f32_16x16x32_bf16 v[52:55], v[180:183], v[152:155], v[52:55]
	global_load_lds_dwordx4 v196, s[4:5]
	s_add_u32 m0, s13, 0xa400
	ds_read_b128 v[132:135], v205 offset:18432
	v_mfma_f32_16x16x32_bf16 v[56:59], v[176:179], v[156:159], v[56:59]
	global_load_lds_dwordx4 v197, s[4:5]
	ds_read_b128 v[112:115], v204 offset:0
	v_mfma_f32_16x16x32_bf16 v[60:63], v[180:183], v[156:159], v[60:63]
	s_add_u32 s2, s2, 0x4000
	s_addc_u32 s3, s3, 0
	ds_read_b128 v[116:119], v204 offset:2048
	v_mfma_f32_16x16x32_bf16 v[32:35], v[184:187], v[160:163], v[32:35]
	s_add_u32 s4, s4, 0x80
	s_addc_u32 s5, s5, 0
	ds_read_b128 v[120:123], v204 offset:4096
	v_mfma_f32_16x16x32_bf16 v[36:39], v[188:191], v[160:163], v[36:39]
	ds_read_b128 v[124:127], v204 offset:6144
	v_mfma_f32_16x16x32_bf16 v[40:43], v[184:187], v[164:167], v[40:43]
	ds_read_b128 v[136:139], v206 offset:16384
	v_mfma_f32_16x16x32_bf16 v[44:47], v[188:191], v[164:167], v[44:47]
	ds_read_b128 v[140:143], v206 offset:18432
	v_mfma_f32_16x16x32_bf16 v[48:51], v[184:187], v[168:171], v[48:51]
	v_mfma_f32_16x16x32_bf16 v[52:55], v[188:191], v[168:171], v[52:55]
	v_mfma_f32_16x16x32_bf16 v[56:59], v[184:187], v[172:175], v[56:59]
	v_mfma_f32_16x16x32_bf16 v[60:63], v[188:191], v[172:175], v[60:63]
	s_waitcnt lgkmcnt(0)
	s_waitcnt vmcnt(0)
	s_barrier
	v_mfma_f32_16x16x32_bf16 v[32:35], v[128:131], v[96:99], v[32:35]
	s_add_u32 m0, s12, 0x0
	ds_read_b128 v[144:147], v203 offset:24576
	v_mfma_f32_16x16x32_bf16 v[36:39], v[132:135], v[96:99], v[36:39]
	global_load_lds_dwordx4 v246, s[2:3]
	s_add_u32 m0, s12, 0x400
	ds_read_b128 v[148:151], v203 offset:26624
	v_mfma_f32_16x16x32_bf16 v[40:43], v[128:131], v[100:103], v[40:43]
	global_load_lds_dwordx4 v247, s[2:3]
	s_add_u32 m0, s12, 0x800
	ds_read_b128 v[152:155], v203 offset:28672
	v_mfma_f32_16x16x32_bf16 v[44:47], v[132:135], v[100:103], v[44:47]
	global_load_lds_dwordx4 v248, s[2:3]
	s_add_u32 m0, s12, 0xc00
	ds_read_b128 v[156:159], v203 offset:30720
	v_mfma_f32_16x16x32_bf16 v[48:51], v[128:131], v[104:107], v[48:51]
	global_load_lds_dwordx4 v249, s[2:3]
	s_add_u32 m0, s13, 0x4000
	ds_read_b128 v[176:179], v205 offset:40960
	v_mfma_f32_16x16x32_bf16 v[52:55], v[132:135], v[104:107], v[52:55]
	global_load_lds_dwordx4 v196, s[4:5]
	s_add_u32 m0, s13, 0x4400
	ds_read_b128 v[180:183], v205 offset:43008
	v_mfma_f32_16x16x32_bf16 v[56:59], v[128:131], v[108:111], v[56:59]
	global_load_lds_dwordx4 v197, s[4:5]
	ds_read_b128 v[160:163], v204 offset:24576
	v_mfma_f32_16x16x32_bf16 v[60:63], v[132:135], v[108:111], v[60:63]
	s_add_u32 s2, s2, 0x4000
	s_addc_u32 s3, s3, 0
	ds_read_b128 v[164:167], v204 offset:26624
	v_mfma_f32_16x16x32_bf16 v[32:35], v[136:139], v[112:115], v[32:35]
	s_add_u32 s4, s4, 0x80
	s_addc_u32 s5, s5, 0
	ds_read_b128 v[168:171], v204 offset:28672
	v_mfma_f32_16x16x32_bf16 v[36:39], v[140:143], v[112:115], v[36:39]
	ds_read_b128 v[172:175], v204 offset:30720
	v_mfma_f32_16x16x32_bf16 v[40:43], v[136:139], v[116:119], v[40:43]
	ds_read_b128 v[184:187], v206 offset:40960
	v_mfma_f32_16x16x32_bf16 v[44:47], v[140:143], v[116:119], v[44:47]
	ds_read_b128 v[188:191], v206 offset:43008
	v_mfma_f32_16x16x32_bf16 v[48:51], v[136:139], v[120:123], v[48:51]
	v_mfma_f32_16x16x32_bf16 v[52:55], v[140:143], v[120:123], v[52:55]
	v_mfma_f32_16x16x32_bf16 v[56:59], v[136:139], v[124:127], v[56:59]
	v_mfma_f32_16x16x32_bf16 v[60:63], v[140:143], v[124:127], v[60:63]
	s_waitcnt lgkmcnt(0)
	s_waitcnt vmcnt(0)
	s_barrier
	v_mfma_f32_16x16x32_bf16 v[32:35], v[176:179], v[144:147], v[32:35]
	s_add_u32 m0, s12, 0x6000
	ds_read_b128 v[96:99], v203 offset:0
	v_mfma_f32_16x16x32_bf16 v[36:39], v[180:183], v[144:147], v[36:39]
	global_load_lds_dwordx4 v246, s[2:3]
	s_add_u32 m0, s12, 0x6400
	ds_read_b128 v[100:103], v203 offset:2048
	v_mfma_f32_16x16x32_bf16 v[40:43], v[176:179], v[148:151], v[40:43]
	global_load_lds_dwordx4 v247, s[2:3]
	s_add_u32 m0, s12, 0x6800
	ds_read_b128 v[104:107], v203 offset:4096
	v_mfma_f32_16x16x32_bf16 v[44:47], v[180:183], v[148:151], v[44:47]
	global_load_lds_dwordx4 v248, s[2:3]
	s_add_u32 m0, s12, 0x6c00
	ds_read_b128 v[108:111], v203 offset:6144
	v_mfma_f32_16x16x32_bf16 v[48:51], v[176:179], v[152:155], v[48:51]
	global_load_lds_dwordx4 v249, s[2:3]
	s_add_u32 m0, s13, 0xa000
	ds_read_b128 v[128:131], v205 offset:16384
	v_mfma_f32_16x16x32_bf16 v[52:55], v[180:183], v[152:155], v[52:55]
	global_load_lds_dwordx4 v196, s[4:5]
	s_add_u32 m0, s13, 0xa400
	ds_read_b128 v[132:135], v205 offset:18432
	v_mfma_f32_16x16x32_bf16 v[56:59], v[176:179], v[156:159], v[56:59]
	global_load_lds_dwordx4 v197, s[4:5]
	ds_read_b128 v[112:115], v204 offset:0
	v_mfma_f32_16x16x32_bf16 v[60:63], v[180:183], v[156:159], v[60:63]
	s_add_u32 s2, s2, 0x4000
	s_addc_u32 s3, s3, 0
	ds_read_b128 v[116:119], v204 offset:2048
	v_mfma_f32_16x16x32_bf16 v[32:35], v[184:187], v[160:163], v[32:35]
	s_add_u32 s4, s4, 0x80
	s_addc_u32 s5, s5, 0
	ds_read_b128 v[120:123], v204 offset:4096
	v_mfma_f32_16x16x32_bf16 v[36:39], v[188:191], v[160:163], v[36:39]
	ds_read_b128 v[124:127], v204 offset:6144
	v_mfma_f32_16x16x32_bf16 v[40:43], v[184:187], v[164:167], v[40:43]
	ds_read_b128 v[136:139], v206 offset:16384
	v_mfma_f32_16x16x32_bf16 v[44:47], v[188:191], v[164:167], v[44:47]
	ds_read_b128 v[140:143], v206 offset:18432
	v_mfma_f32_16x16x32_bf16 v[48:51], v[184:187], v[168:171], v[48:51]
	v_mfma_f32_16x16x32_bf16 v[52:55], v[188:191], v[168:171], v[52:55]
	v_mfma_f32_16x16x32_bf16 v[56:59], v[184:187], v[172:175], v[56:59]
	v_mfma_f32_16x16x32_bf16 v[60:63], v[188:191], v[172:175], v[60:63]
	s_waitcnt lgkmcnt(0)
	s_waitcnt vmcnt(0)
	s_barrier
	v_mfma_f32_16x16x32_bf16 v[32:35], v[128:131], v[96:99], v[32:35]
	s_add_u32 m0, s12, 0x0
	ds_read_b128 v[144:147], v203 offset:24576
	v_mfma_f32_16x16x32_bf16 v[36:39], v[132:135], v[96:99], v[36:39]
	global_load_lds_dwordx4 v246, s[2:3]
	s_add_u32 m0, s12, 0x400
	ds_read_b128 v[148:151], v203 offset:26624
	v_mfma_f32_16x16x32_bf16 v[40:43], v[128:131], v[100:103], v[40:43]
	global_load_lds_dwordx4 v247, s[2:3]
	s_add_u32 m0, s12, 0x800
	ds_read_b128 v[152:155], v203 offset:28672
	v_mfma_f32_16x16x32_bf16 v[44:47], v[132:135], v[100:103], v[44:47]
	global_load_lds_dwordx4 v248, s[2:3]
	s_add_u32 m0, s12, 0xc00
	ds_read_b128 v[156:159], v203 offset:30720
	v_mfma_f32_16x16x32_bf16 v[48:51], v[128:131], v[104:107], v[48:51]
	global_load_lds_dwordx4 v249, s[2:3]
	s_add_u32 m0, s13, 0x4000
	ds_read_b128 v[176:179], v205 offset:40960
	v_mfma_f32_16x16x32_bf16 v[52:55], v[132:135], v[104:107], v[52:55]
	global_load_lds_dwordx4 v196, s[4:5]
	s_add_u32 m0, s13, 0x4400
	ds_read_b128 v[180:183], v205 offset:43008
	v_mfma_f32_16x16x32_bf16 v[56:59], v[128:131], v[108:111], v[56:59]
	global_load_lds_dwordx4 v197, s[4:5]
	ds_read_b128 v[160:163], v204 offset:24576
	v_mfma_f32_16x16x32_bf16 v[60:63], v[132:135], v[108:111], v[60:63]
	s_add_u32 s2, s2, 0x4000
	s_addc_u32 s3, s3, 0
	ds_read_b128 v[164:167], v204 offset:26624
	v_mfma_f32_16x16x32_bf16 v[32:35], v[136:139], v[112:115], v[32:35]
	s_add_u32 s4, s4, 0x80
	s_addc_u32 s5, s5, 0
	ds_read_b128 v[168:171], v204 offset:28672
	v_mfma_f32_16x16x32_bf16 v[36:39], v[140:143], v[112:115], v[36:39]
	ds_read_b128 v[172:175], v204 offset:30720
	v_mfma_f32_16x16x32_bf16 v[40:43], v[136:139], v[116:119], v[40:43]
	ds_read_b128 v[184:187], v206 offset:40960
	v_mfma_f32_16x16x32_bf16 v[44:47], v[140:143], v[116:119], v[44:47]
	ds_read_b128 v[188:191], v206 offset:43008
	v_mfma_f32_16x16x32_bf16 v[48:51], v[136:139], v[120:123], v[48:51]
	v_mfma_f32_16x16x32_bf16 v[52:55], v[140:143], v[120:123], v[52:55]
	v_mfma_f32_16x16x32_bf16 v[56:59], v[136:139], v[124:127], v[56:59]
	v_mfma_f32_16x16x32_bf16 v[60:63], v[140:143], v[124:127], v[60:63]
	s_waitcnt lgkmcnt(0)
	s_waitcnt vmcnt(0)
	s_barrier
	v_mfma_f32_16x16x32_bf16 v[32:35], v[176:179], v[144:147], v[32:35]
	s_add_u32 m0, s12, 0x6000
	ds_read_b128 v[96:99], v203 offset:0
	v_mfma_f32_16x16x32_bf16 v[36:39], v[180:183], v[144:147], v[36:39]
	global_load_lds_dwordx4 v246, s[2:3]
	s_add_u32 m0, s12, 0x6400
	ds_read_b128 v[100:103], v203 offset:2048
	v_mfma_f32_16x16x32_bf16 v[40:43], v[176:179], v[148:151], v[40:43]
	global_load_lds_dwordx4 v247, s[2:3]
	s_add_u32 m0, s12, 0x6800
	ds_read_b128 v[104:107], v203 offset:4096
	v_mfma_f32_16x16x32_bf16 v[44:47], v[180:183], v[148:151], v[44:47]
	global_load_lds_dwordx4 v248, s[2:3]
	s_add_u32 m0, s12, 0x6c00
	ds_read_b128 v[108:111], v203 offset:6144
	v_mfma_f32_16x16x32_bf16 v[48:51], v[176:179], v[152:155], v[48:51]
	global_load_lds_dwordx4 v249, s[2:3]
	s_add_u32 m0, s13, 0xa000
	ds_read_b128 v[128:131], v205 offset:16384
	v_mfma_f32_16x16x32_bf16 v[52:55], v[180:183], v[152:155], v[52:55]
	global_load_lds_dwordx4 v196, s[4:5]
	s_add_u32 m0, s13, 0xa400
	ds_read_b128 v[132:135], v205 offset:18432
	v_mfma_f32_16x16x32_bf16 v[56:59], v[176:179], v[156:159], v[56:59]
	global_load_lds_dwordx4 v197, s[4:5]
	ds_read_b128 v[112:115], v204 offset:0
	v_mfma_f32_16x16x32_bf16 v[60:63], v[180:183], v[156:159], v[60:63]
	s_add_u32 s2, s2, 0x4000
	s_addc_u32 s3, s3, 0
	ds_read_b128 v[116:119], v204 offset:2048
	v_mfma_f32_16x16x32_bf16 v[32:35], v[184:187], v[160:163], v[32:35]
	s_add_u32 s4, s4, 0x80
	s_addc_u32 s5, s5, 0
	ds_read_b128 v[120:123], v204 offset:4096
	v_mfma_f32_16x16x32_bf16 v[36:39], v[188:191], v[160:163], v[36:39]
	ds_read_b128 v[124:127], v204 offset:6144
	v_mfma_f32_16x16x32_bf16 v[40:43], v[184:187], v[164:167], v[40:43]
	ds_read_b128 v[136:139], v206 offset:16384
	v_mfma_f32_16x16x32_bf16 v[44:47], v[188:191], v[164:167], v[44:47]
	ds_read_b128 v[140:143], v206 offset:18432
	v_mfma_f32_16x16x32_bf16 v[48:51], v[184:187], v[168:171], v[48:51]
	v_mfma_f32_16x16x32_bf16 v[52:55], v[188:191], v[168:171], v[52:55]
	v_mfma_f32_16x16x32_bf16 v[56:59], v[184:187], v[172:175], v[56:59]
	v_mfma_f32_16x16x32_bf16 v[60:63], v[188:191], v[172:175], v[60:63]
	s_waitcnt lgkmcnt(0)
	s_waitcnt vmcnt(0)
	s_barrier
	v_mfma_f32_16x16x32_bf16 v[32:35], v[128:131], v[96:99], v[32:35]
	s_add_u32 m0, s12, 0x0
	ds_read_b128 v[144:147], v203 offset:24576
	v_mfma_f32_16x16x32_bf16 v[36:39], v[132:135], v[96:99], v[36:39]
	global_load_lds_dwordx4 v246, s[2:3]
	s_add_u32 m0, s12, 0x400
	ds_read_b128 v[148:151], v203 offset:26624
	v_mfma_f32_16x16x32_bf16 v[40:43], v[128:131], v[100:103], v[40:43]
	global_load_lds_dwordx4 v247, s[2:3]
	s_add_u32 m0, s12, 0x800
	ds_read_b128 v[152:155], v203 offset:28672
	v_mfma_f32_16x16x32_bf16 v[44:47], v[132:135], v[100:103], v[44:47]
	global_load_lds_dwordx4 v248, s[2:3]
	s_add_u32 m0, s12, 0xc00
	ds_read_b128 v[156:159], v203 offset:30720
	v_mfma_f32_16x16x32_bf16 v[48:51], v[128:131], v[104:107], v[48:51]
	global_load_lds_dwordx4 v249, s[2:3]
	s_add_u32 m0, s13, 0x4000
	ds_read_b128 v[176:179], v205 offset:40960
	v_mfma_f32_16x16x32_bf16 v[52:55], v[132:135], v[104:107], v[52:55]
	global_load_lds_dwordx4 v196, s[4:5]
	s_add_u32 m0, s13, 0x4400
	ds_read_b128 v[180:183], v205 offset:43008
	v_mfma_f32_16x16x32_bf16 v[56:59], v[128:131], v[108:111], v[56:59]
	global_load_lds_dwordx4 v197, s[4:5]
	ds_read_b128 v[160:163], v204 offset:24576
	v_mfma_f32_16x16x32_bf16 v[60:63], v[132:135], v[108:111], v[60:63]
	s_add_u32 s2, s2, 0x4000
	s_addc_u32 s3, s3, 0
	ds_read_b128 v[164:167], v204 offset:26624
	v_mfma_f32_16x16x32_bf16 v[32:35], v[136:139], v[112:115], v[32:35]
	s_add_u32 s4, s4, 0x80
	s_addc_u32 s5, s5, 0
	ds_read_b128 v[168:171], v204 offset:28672
	v_mfma_f32_16x16x32_bf16 v[36:39], v[140:143], v[112:115], v[36:39]
	ds_read_b128 v[172:175], v204 offset:30720
	v_mfma_f32_16x16x32_bf16 v[40:43], v[136:139], v[116:119], v[40:43]
	ds_read_b128 v[184:187], v206 offset:40960
	v_mfma_f32_16x16x32_bf16 v[44:47], v[140:143], v[116:119], v[44:47]
	ds_read_b128 v[188:191], v206 offset:43008
	v_mfma_f32_16x16x32_bf16 v[48:51], v[136:139], v[120:123], v[48:51]
	v_mfma_f32_16x16x32_bf16 v[52:55], v[140:143], v[120:123], v[52:55]
	v_mfma_f32_16x16x32_bf16 v[56:59], v[136:139], v[124:127], v[56:59]
	v_mfma_f32_16x16x32_bf16 v[60:63], v[140:143], v[124:127], v[60:63]
	s_waitcnt lgkmcnt(0)
	s_waitcnt vmcnt(0)
	s_barrier
	v_mfma_f32_16x16x32_bf16 v[32:35], v[176:179], v[144:147], v[32:35]
	s_add_u32 m0, s12, 0x6000
	ds_read_b128 v[96:99], v203 offset:0
	v_mfma_f32_16x16x32_bf16 v[36:39], v[180:183], v[144:147], v[36:39]
	global_load_lds_dwordx4 v246, s[2:3]
	s_add_u32 m0, s12, 0x6400
	ds_read_b128 v[100:103], v203 offset:2048
	v_mfma_f32_16x16x32_bf16 v[40:43], v[176:179], v[148:151], v[40:43]
	global_load_lds_dwordx4 v247, s[2:3]
	s_add_u32 m0, s12, 0x6800
	ds_read_b128 v[104:107], v203 offset:4096
	v_mfma_f32_16x16x32_bf16 v[44:47], v[180:183], v[148:151], v[44:47]
	global_load_lds_dwordx4 v248, s[2:3]
	s_add_u32 m0, s12, 0x6c00
	ds_read_b128 v[108:111], v203 offset:6144
	v_mfma_f32_16x16x32_bf16 v[48:51], v[176:179], v[152:155], v[48:51]
	global_load_lds_dwordx4 v249, s[2:3]
	s_add_u32 m0, s13, 0xa000
	ds_read_b128 v[128:131], v205 offset:16384
	v_mfma_f32_16x16x32_bf16 v[52:55], v[180:183], v[152:155], v[52:55]
	global_load_lds_dwordx4 v196, s[4:5]
	s_add_u32 m0, s13, 0xa400
	ds_read_b128 v[132:135], v205 offset:18432
	v_mfma_f32_16x16x32_bf16 v[56:59], v[176:179], v[156:159], v[56:59]
	global_load_lds_dwordx4 v197, s[4:5]
	ds_read_b128 v[112:115], v204 offset:0
	v_mfma_f32_16x16x32_bf16 v[60:63], v[180:183], v[156:159], v[60:63]
	s_add_u32 s2, s2, 0x4000
	s_addc_u32 s3, s3, 0
	ds_read_b128 v[116:119], v204 offset:2048
	v_mfma_f32_16x16x32_bf16 v[32:35], v[184:187], v[160:163], v[32:35]
	s_add_u32 s4, s4, 0x80
	s_addc_u32 s5, s5, 0
	ds_read_b128 v[120:123], v204 offset:4096
	v_mfma_f32_16x16x32_bf16 v[36:39], v[188:191], v[160:163], v[36:39]
	ds_read_b128 v[124:127], v204 offset:6144
	v_mfma_f32_16x16x32_bf16 v[40:43], v[184:187], v[164:167], v[40:43]
	ds_read_b128 v[136:139], v206 offset:16384
	v_mfma_f32_16x16x32_bf16 v[44:47], v[188:191], v[164:167], v[44:47]
	ds_read_b128 v[140:143], v206 offset:18432
	v_mfma_f32_16x16x32_bf16 v[48:51], v[184:187], v[168:171], v[48:51]
	v_mfma_f32_16x16x32_bf16 v[52:55], v[188:191], v[168:171], v[52:55]
	v_mfma_f32_16x16x32_bf16 v[56:59], v[184:187], v[172:175], v[56:59]
	v_mfma_f32_16x16x32_bf16 v[60:63], v[188:191], v[172:175], v[60:63]
	s_waitcnt lgkmcnt(0)
	s_waitcnt vmcnt(0)
	s_barrier
	v_mfma_f32_16x16x32_bf16 v[32:35], v[128:131], v[96:99], v[32:35]
	s_add_u32 m0, s12, 0x0
	ds_read_b128 v[144:147], v203 offset:24576
	v_mfma_f32_16x16x32_bf16 v[36:39], v[132:135], v[96:99], v[36:39]
	global_load_lds_dwordx4 v246, s[2:3]
	s_add_u32 m0, s12, 0x400
	ds_read_b128 v[148:151], v203 offset:26624
	v_mfma_f32_16x16x32_bf16 v[40:43], v[128:131], v[100:103], v[40:43]
	global_load_lds_dwordx4 v247, s[2:3]
	s_add_u32 m0, s12, 0x800
	ds_read_b128 v[152:155], v203 offset:28672
	v_mfma_f32_16x16x32_bf16 v[44:47], v[132:135], v[100:103], v[44:47]
	global_load_lds_dwordx4 v248, s[2:3]
	s_add_u32 m0, s12, 0xc00
	ds_read_b128 v[156:159], v203 offset:30720
	v_mfma_f32_16x16x32_bf16 v[48:51], v[128:131], v[104:107], v[48:51]
	global_load_lds_dwordx4 v249, s[2:3]
	s_add_u32 m0, s13, 0x4000
	ds_read_b128 v[176:179], v205 offset:40960
	v_mfma_f32_16x16x32_bf16 v[52:55], v[132:135], v[104:107], v[52:55]
	global_load_lds_dwordx4 v196, s[4:5]
	s_add_u32 m0, s13, 0x4400
	ds_read_b128 v[180:183], v205 offset:43008
	v_mfma_f32_16x16x32_bf16 v[56:59], v[128:131], v[108:111], v[56:59]
	global_load_lds_dwordx4 v197, s[4:5]
	ds_read_b128 v[160:163], v204 offset:24576
	v_mfma_f32_16x16x32_bf16 v[60:63], v[132:135], v[108:111], v[60:63]
	s_add_u32 s2, s2, 0x4000
	s_addc_u32 s3, s3, 0
	ds_read_b128 v[164:167], v204 offset:26624
	v_mfma_f32_16x16x32_bf16 v[32:35], v[136:139], v[112:115], v[32:35]
	s_add_u32 s4, s4, 0x80
	s_addc_u32 s5, s5, 0
	ds_read_b128 v[168:171], v204 offset:28672
	v_mfma_f32_16x16x32_bf16 v[36:39], v[140:143], v[112:115], v[36:39]
	ds_read_b128 v[172:175], v204 offset:30720
	v_mfma_f32_16x16x32_bf16 v[40:43], v[136:139], v[116:119], v[40:43]
	ds_read_b128 v[184:187], v206 offset:40960
	v_mfma_f32_16x16x32_bf16 v[44:47], v[140:143], v[116:119], v[44:47]
	ds_read_b128 v[188:191], v206 offset:43008
	v_mfma_f32_16x16x32_bf16 v[48:51], v[136:139], v[120:123], v[48:51]
	v_mfma_f32_16x16x32_bf16 v[52:55], v[140:143], v[120:123], v[52:55]
	v_mfma_f32_16x16x32_bf16 v[56:59], v[136:139], v[124:127], v[56:59]
	v_mfma_f32_16x16x32_bf16 v[60:63], v[140:143], v[124:127], v[60:63]
	s_waitcnt lgkmcnt(0)
	s_waitcnt vmcnt(0)
	s_barrier
	v_mfma_f32_16x16x32_bf16 v[32:35], v[176:179], v[144:147], v[32:35]
	s_add_u32 m0, s12, 0x6000
	ds_read_b128 v[96:99], v203 offset:0
	v_mfma_f32_16x16x32_bf16 v[36:39], v[180:183], v[144:147], v[36:39]
	global_load_lds_dwordx4 v246, s[2:3]
	s_add_u32 m0, s12, 0x6400
	ds_read_b128 v[100:103], v203 offset:2048
	v_mfma_f32_16x16x32_bf16 v[40:43], v[176:179], v[148:151], v[40:43]
	global_load_lds_dwordx4 v247, s[2:3]
	s_add_u32 m0, s12, 0x6800
	ds_read_b128 v[104:107], v203 offset:4096
	v_mfma_f32_16x16x32_bf16 v[44:47], v[180:183], v[148:151], v[44:47]
	global_load_lds_dwordx4 v248, s[2:3]
	s_add_u32 m0, s12, 0x6c00
	ds_read_b128 v[108:111], v203 offset:6144
	v_mfma_f32_16x16x32_bf16 v[48:51], v[176:179], v[152:155], v[48:51]
	global_load_lds_dwordx4 v249, s[2:3]
	s_add_u32 m0, s13, 0xa000
	ds_read_b128 v[128:131], v205 offset:16384
	v_mfma_f32_16x16x32_bf16 v[52:55], v[180:183], v[152:155], v[52:55]
	global_load_lds_dwordx4 v196, s[4:5]
	s_add_u32 m0, s13, 0xa400
	ds_read_b128 v[132:135], v205 offset:18432
	v_mfma_f32_16x16x32_bf16 v[56:59], v[176:179], v[156:159], v[56:59]
	global_load_lds_dwordx4 v197, s[4:5]
	ds_read_b128 v[112:115], v204 offset:0
	v_mfma_f32_16x16x32_bf16 v[60:63], v[180:183], v[156:159], v[60:63]
	s_add_u32 s2, s2, 0x4000
	s_addc_u32 s3, s3, 0
	ds_read_b128 v[116:119], v204 offset:2048
	v_mfma_f32_16x16x32_bf16 v[32:35], v[184:187], v[160:163], v[32:35]
	s_add_u32 s4, s4, 0x80
	s_addc_u32 s5, s5, 0
	ds_read_b128 v[120:123], v204 offset:4096
	v_mfma_f32_16x16x32_bf16 v[36:39], v[188:191], v[160:163], v[36:39]
	ds_read_b128 v[124:127], v204 offset:6144
	v_mfma_f32_16x16x32_bf16 v[40:43], v[184:187], v[164:167], v[40:43]
	ds_read_b128 v[136:139], v206 offset:16384
	v_mfma_f32_16x16x32_bf16 v[44:47], v[188:191], v[164:167], v[44:47]
	ds_read_b128 v[140:143], v206 offset:18432
	v_mfma_f32_16x16x32_bf16 v[48:51], v[184:187], v[168:171], v[48:51]
	v_mfma_f32_16x16x32_bf16 v[52:55], v[188:191], v[168:171], v[52:55]
	v_mfma_f32_16x16x32_bf16 v[56:59], v[184:187], v[172:175], v[56:59]
	v_mfma_f32_16x16x32_bf16 v[60:63], v[188:191], v[172:175], v[60:63]
	s_waitcnt lgkmcnt(0)
	s_waitcnt vmcnt(0)
	s_barrier
	v_mfma_f32_16x16x32_bf16 v[32:35], v[128:131], v[96:99], v[32:35]
	s_add_u32 m0, s12, 0x0
	ds_read_b128 v[144:147], v203 offset:24576
	v_mfma_f32_16x16x32_bf16 v[36:39], v[132:135], v[96:99], v[36:39]
	global_load_lds_dwordx4 v192, s[8:9]
	s_add_u32 m0, s12, 0x400
	ds_read_b128 v[148:151], v203 offset:26624
	v_mfma_f32_16x16x32_bf16 v[40:43], v[128:131], v[100:103], v[40:43]
	global_load_lds_dwordx4 v193, s[8:9]
	s_add_u32 m0, s12, 0x800
	ds_read_b128 v[152:155], v203 offset:28672
	v_mfma_f32_16x16x32_bf16 v[44:47], v[132:135], v[100:103], v[44:47]
	global_load_lds_dwordx4 v194, s[8:9]
	s_add_u32 m0, s12, 0xc00
	ds_read_b128 v[156:159], v203 offset:30720
	v_mfma_f32_16x16x32_bf16 v[48:51], v[128:131], v[104:107], v[48:51]
	global_load_lds_dwordx4 v195, s[8:9]
	s_add_u32 m0, s13, 0x4000
	ds_read_b128 v[176:179], v205 offset:40960
	v_mfma_f32_16x16x32_bf16 v[52:55], v[132:135], v[104:107], v[52:55]
	global_load_lds_dwordx4 v198, s[10:11]
	s_add_u32 m0, s13, 0x4400
	ds_read_b128 v[180:183], v205 offset:43008
	v_mfma_f32_16x16x32_bf16 v[56:59], v[128:131], v[108:111], v[56:59]
	global_load_lds_dwordx4 v199, s[10:11]
	ds_read_b128 v[160:163], v204 offset:24576
	v_mfma_f32_16x16x32_bf16 v[60:63], v[132:135], v[108:111], v[60:63]
	s_add_u32 s8, s8, 0x80
	s_addc_u32 s9, s9, 0
	ds_read_b128 v[164:167], v204 offset:26624
	v_mfma_f32_16x16x32_bf16 v[32:35], v[136:139], v[112:115], v[32:35]
	s_add_u32 s10, s10, 0x80
	s_addc_u32 s11, s11, 0
	ds_read_b128 v[168:171], v204 offset:28672
	v_mfma_f32_16x16x32_bf16 v[36:39], v[140:143], v[112:115], v[36:39]
	s_sub_u32 s2, s2, 0x40000
	s_subb_u32 s3, s3, 0
	ds_read_b128 v[172:175], v204 offset:30720
	v_mfma_f32_16x16x32_bf16 v[40:43], v[136:139], v[116:119], v[40:43]
	s_add_u32 s4, s4, 0x1ff800
	s_addc_u32 s5, s5, 0
	ds_read_b128 v[184:187], v206 offset:40960
	v_mfma_f32_16x16x32_bf16 v[44:47], v[140:143], v[116:119], v[44:47]
	ds_read_b128 v[188:191], v206 offset:43008
	v_mfma_f32_16x16x32_bf16 v[48:51], v[136:139], v[120:123], v[48:51]
	v_mfma_f32_16x16x32_bf16 v[52:55], v[140:143], v[120:123], v[52:55]
	v_mfma_f32_16x16x32_bf16 v[56:59], v[136:139], v[124:127], v[56:59]
	v_mfma_f32_16x16x32_bf16 v[60:63], v[140:143], v[124:127], v[60:63]
	s_waitcnt lgkmcnt(0)
	s_waitcnt vmcnt(0)
	s_barrier
	v_mfma_f32_16x16x32_bf16 v[32:35], v[176:179], v[144:147], v[32:35]
	s_add_u32 m0, s12, 0x6000
	ds_read_b128 v[96:99], v203 offset:0
	v_mfma_f32_16x16x32_bf16 v[36:39], v[180:183], v[144:147], v[36:39]
	global_load_lds_dwordx4 v192, s[8:9]
	s_add_u32 m0, s12, 0x6400
	ds_read_b128 v[100:103], v203 offset:2048
	v_mfma_f32_16x16x32_bf16 v[40:43], v[176:179], v[148:151], v[40:43]
	global_load_lds_dwordx4 v193, s[8:9]
	s_add_u32 m0, s12, 0x6800
	ds_read_b128 v[104:107], v203 offset:4096
	v_mfma_f32_16x16x32_bf16 v[44:47], v[180:183], v[148:151], v[44:47]
	global_load_lds_dwordx4 v194, s[8:9]
	s_add_u32 m0, s12, 0x6c00
	ds_read_b128 v[108:111], v203 offset:6144
	v_mfma_f32_16x16x32_bf16 v[48:51], v[176:179], v[152:155], v[48:51]
	global_load_lds_dwordx4 v195, s[8:9]
	s_add_u32 m0, s13, 0xa000
	ds_read_b128 v[128:131], v205 offset:16384
	v_mfma_f32_16x16x32_bf16 v[52:55], v[180:183], v[152:155], v[52:55]
	global_load_lds_dwordx4 v198, s[10:11]
	s_add_u32 m0, s13, 0xa400
	ds_read_b128 v[132:135], v205 offset:18432
	v_mfma_f32_16x16x32_bf16 v[56:59], v[176:179], v[156:159], v[56:59]
	global_load_lds_dwordx4 v199, s[10:11]
	ds_read_b128 v[112:115], v204 offset:0
	v_mfma_f32_16x16x32_bf16 v[60:63], v[180:183], v[156:159], v[60:63]
	s_add_u32 s8, s8, 0x80
	s_addc_u32 s9, s9, 0
	ds_read_b128 v[116:119], v204 offset:2048
	v_mfma_f32_16x16x32_bf16 v[32:35], v[184:187], v[160:163], v[32:35]
	s_add_u32 s10, s10, 0x80
	s_addc_u32 s11, s11, 0
	ds_read_b128 v[120:123], v204 offset:4096
	v_mfma_f32_16x16x32_bf16 v[36:39], v[188:191], v[160:163], v[36:39]
	ds_read_b128 v[124:127], v204 offset:6144
	v_mfma_f32_16x16x32_bf16 v[40:43], v[184:187], v[164:167], v[40:43]
	ds_read_b128 v[136:139], v206 offset:16384
	v_mfma_f32_16x16x32_bf16 v[44:47], v[188:191], v[164:167], v[44:47]
	ds_read_b128 v[140:143], v206 offset:18432
	v_mfma_f32_16x16x32_bf16 v[48:51], v[184:187], v[168:171], v[48:51]
	v_mfma_f32_16x16x32_bf16 v[52:55], v[188:191], v[168:171], v[52:55]
	v_mfma_f32_16x16x32_bf16 v[56:59], v[184:187], v[172:175], v[56:59]
	v_mfma_f32_16x16x32_bf16 v[60:63], v[188:191], v[172:175], v[60:63]
	s_waitcnt lgkmcnt(0)
	s_nop 7
	s_nop 1
	v_mul_f32_e32 v64, 0xbfb8aa3b, v32
	s_nop 0
	v_exp_f32_e32 v64, v64
	s_nop 0
	v_add_f32_e32 v64, 1.0, v64
	s_nop 0
	v_div_scale_f32 v200, s[14:15], v64, v64, 1.0
	s_nop 0
	v_rcp_f32_e32 v207, v200
	s_nop 0
	v_fma_f32 v208, -v200, v207, 1.0
	s_nop 0
	v_fmac_f32_e32 v207, v208, v207
	s_nop 0
	v_div_scale_f32 v208, vcc, 1.0, v64, 1.0
	s_nop 0
	v_mul_f32_e32 v209, v208, v207
	v_mul_f32_e32 v65, 0xbfb8aa3b, v33
	v_fma_f32 v210, -v200, v209, v208
	v_exp_f32_e32 v65, v65
	v_fmac_f32_e32 v209, v210, v207
	v_add_f32_e32 v65, 1.0, v65
	v_fma_f32 v200, -v200, v209, v208
	v_div_scale_f32 v211, s[14:15], v65, v65, 1.0
	v_div_fmas_f32 v200, v200, v207, v209
	v_rcp_f32_e32 v212, v211
	v_div_fixup_f32 v64, v200, v64, 1.0
	v_fma_f32 v213, -v211, v212, 1.0
	v_bfe_u32 v200, v64, 16, 1
	v_fmac_f32_e32 v212, v213, v212
	v_add3_u32 v64, v64, v200, s69
	v_div_scale_f32 v213, vcc, 1.0, v65, 1.0
	v_and_b32_e32 v64, 0xffff0000, v64
	v_mul_f32_e32 v214, v213, v212
	v_mul_f32_e32 v66, 0xbfb8aa3b, v34
	v_fma_f32 v215, -v211, v214, v213
	v_exp_f32_e32 v66, v66
	v_fmac_f32_e32 v214, v215, v212
	v_add_f32_e32 v66, 1.0, v66
	v_fma_f32 v211, -v211, v214, v213
	v_div_scale_f32 v200, s[14:15], v66, v66, 1.0
	v_div_fmas_f32 v211, v211, v212, v214
	v_rcp_f32_e32 v207, v200
	v_div_fixup_f32 v65, v211, v65, 1.0
	v_fma_f32 v208, -v200, v207, 1.0
	v_bfe_u32 v211, v65, 16, 1
	v_fmac_f32_e32 v207, v208, v207
	v_add3_u32 v65, v65, v211, s69
	v_div_scale_f32 v208, vcc, 1.0, v66, 1.0
	v_and_b32_e32 v65, 0xffff0000, v65
	v_mul_f32_e32 v209, v208, v207
	v_mul_f32_e32 v67, 0xbfb8aa3b, v35
	v_fma_f32 v210, -v200, v209, v208
	v_exp_f32_e32 v67, v67
	v_fmac_f32_e32 v209, v210, v207
	v_add_f32_e32 v67, 1.0, v67
	v_fma_f32 v200, -v200, v209, v208
	v_div_scale_f32 v211, s[14:15], v67, v67, 1.0
	v_div_fmas_f32 v200, v200, v207, v209
	v_rcp_f32_e32 v212, v211
	v_div_fixup_f32 v66, v200, v66, 1.0
	v_fma_f32 v213, -v211, v212, 1.0
	v_bfe_u32 v200, v66, 16, 1
	v_fmac_f32_e32 v212, v213, v212
	v_add3_u32 v66, v66, v200, s69
	v_div_scale_f32 v213, vcc, 1.0, v67, 1.0
	v_and_b32_e32 v66, 0xffff0000, v66
	v_mul_f32_e32 v214, v213, v212
	v_mul_f32_e32 v68, 0xbfb8aa3b, v36
	v_fma_f32 v215, -v211, v214, v213
	v_exp_f32_e32 v68, v68
	v_fmac_f32_e32 v214, v215, v212
	v_add_f32_e32 v68, 1.0, v68
	v_fma_f32 v211, -v211, v214, v213
	v_div_scale_f32 v200, s[14:15], v68, v68, 1.0
	v_div_fmas_f32 v211, v211, v212, v214
	v_rcp_f32_e32 v207, v200
	v_div_fixup_f32 v67, v211, v67, 1.0
	v_fma_f32 v208, -v200, v207, 1.0
	v_bfe_u32 v211, v67, 16, 1
	v_fmac_f32_e32 v207, v208, v207
	v_add3_u32 v67, v67, v211, s69
	v_div_scale_f32 v208, vcc, 1.0, v68, 1.0
	v_and_b32_e32 v67, 0xffff0000, v67
	v_mul_f32_e32 v209, v208, v207
	v_mul_f32_e32 v69, 0xbfb8aa3b, v37
	v_fma_f32 v210, -v200, v209, v208
	v_exp_f32_e32 v69, v69
	v_fmac_f32_e32 v209, v210, v207
	v_add_f32_e32 v69, 1.0, v69
	v_fma_f32 v200, -v200, v209, v208
	v_div_scale_f32 v211, s[14:15], v69, v69, 1.0
	v_div_fmas_f32 v200, v200, v207, v209
	v_rcp_f32_e32 v212, v211
	v_div_fixup_f32 v68, v200, v68, 1.0
	v_fma_f32 v213, -v211, v212, 1.0
	v_bfe_u32 v200, v68, 16, 1
	v_fmac_f32_e32 v212, v213, v212
	v_add3_u32 v68, v68, v200, s69
	v_div_scale_f32 v213, vcc, 1.0, v69, 1.0
	v_and_b32_e32 v68, 0xffff0000, v68
	v_mul_f32_e32 v214, v213, v212
	v_mul_f32_e32 v70, 0xbfb8aa3b, v38
	v_fma_f32 v215, -v211, v214, v213
	v_exp_f32_e32 v70, v70
	v_fmac_f32_e32 v214, v215, v212
	v_add_f32_e32 v70, 1.0, v70
	v_fma_f32 v211, -v211, v214, v213
	v_div_scale_f32 v200, s[14:15], v70, v70, 1.0
	v_div_fmas_f32 v211, v211, v212, v214
	v_rcp_f32_e32 v207, v200
	v_div_fixup_f32 v69, v211, v69, 1.0
	v_fma_f32 v208, -v200, v207, 1.0
	v_bfe_u32 v211, v69, 16, 1
	v_fmac_f32_e32 v207, v208, v207
	v_add3_u32 v69, v69, v211, s69
	v_div_scale_f32 v208, vcc, 1.0, v70, 1.0
	v_and_b32_e32 v69, 0xffff0000, v69
	v_mul_f32_e32 v209, v208, v207
	v_mul_f32_e32 v71, 0xbfb8aa3b, v39
	v_fma_f32 v210, -v200, v209, v208
	v_exp_f32_e32 v71, v71
	v_fmac_f32_e32 v209, v210, v207
	v_add_f32_e32 v71, 1.0, v71
	v_fma_f32 v200, -v200, v209, v208
	v_div_scale_f32 v211, s[14:15], v71, v71, 1.0
	v_div_fmas_f32 v200, v200, v207, v209
	v_rcp_f32_e32 v212, v211
	v_div_fixup_f32 v70, v200, v70, 1.0
	v_fma_f32 v213, -v211, v212, 1.0
	v_bfe_u32 v200, v70, 16, 1
	v_fmac_f32_e32 v212, v213, v212
	v_add3_u32 v70, v70, v200, s69
	v_div_scale_f32 v213, vcc, 1.0, v71, 1.0
	v_and_b32_e32 v70, 0xffff0000, v70
	v_mul_f32_e32 v214, v213, v212
	v_mul_f32_e32 v72, 0xbfb8aa3b, v40
	v_fma_f32 v215, -v211, v214, v213
	v_exp_f32_e32 v72, v72
	v_fmac_f32_e32 v214, v215, v212
	v_add_f32_e32 v72, 1.0, v72
	v_fma_f32 v211, -v211, v214, v213
	v_div_scale_f32 v200, s[14:15], v72, v72, 1.0
	v_div_fmas_f32 v211, v211, v212, v214
	v_rcp_f32_e32 v207, v200
	v_div_fixup_f32 v71, v211, v71, 1.0
	v_fma_f32 v208, -v200, v207, 1.0
	v_bfe_u32 v211, v71, 16, 1
	v_fmac_f32_e32 v207, v208, v207
	v_add3_u32 v71, v71, v211, s69
	v_div_scale_f32 v208, vcc, 1.0, v72, 1.0
	v_and_b32_e32 v71, 0xffff0000, v71
	v_mul_f32_e32 v209, v208, v207
	v_mul_f32_e32 v73, 0xbfb8aa3b, v41
	v_fma_f32 v210, -v200, v209, v208
	v_exp_f32_e32 v73, v73
	v_fmac_f32_e32 v209, v210, v207
	v_add_f32_e32 v73, 1.0, v73
	v_fma_f32 v200, -v200, v209, v208
	v_div_scale_f32 v211, s[14:15], v73, v73, 1.0
	v_div_fmas_f32 v200, v200, v207, v209
	v_rcp_f32_e32 v212, v211
	v_div_fixup_f32 v72, v200, v72, 1.0
	v_fma_f32 v213, -v211, v212, 1.0
	v_bfe_u32 v200, v72, 16, 1
	v_fmac_f32_e32 v212, v213, v212
	v_add3_u32 v72, v72, v200, s69
	v_div_scale_f32 v213, vcc, 1.0, v73, 1.0
	v_and_b32_e32 v72, 0xffff0000, v72
	v_mul_f32_e32 v214, v213, v212
	v_mul_f32_e32 v74, 0xbfb8aa3b, v42
	v_fma_f32 v215, -v211, v214, v213
	v_exp_f32_e32 v74, v74
	v_fmac_f32_e32 v214, v215, v212
	v_add_f32_e32 v74, 1.0, v74
	v_fma_f32 v211, -v211, v214, v213
	v_div_scale_f32 v200, s[14:15], v74, v74, 1.0
	v_div_fmas_f32 v211, v211, v212, v214
	v_rcp_f32_e32 v207, v200
	v_div_fixup_f32 v73, v211, v73, 1.0
	v_fma_f32 v208, -v200, v207, 1.0
	v_bfe_u32 v211, v73, 16, 1
	v_fmac_f32_e32 v207, v208, v207
	v_add3_u32 v73, v73, v211, s69
	v_div_scale_f32 v208, vcc, 1.0, v74, 1.0
	v_and_b32_e32 v73, 0xffff0000, v73
	v_mul_f32_e32 v209, v208, v207
	v_mul_f32_e32 v75, 0xbfb8aa3b, v43
	v_fma_f32 v210, -v200, v209, v208
	v_exp_f32_e32 v75, v75
	v_fmac_f32_e32 v209, v210, v207
	v_add_f32_e32 v75, 1.0, v75
	v_fma_f32 v200, -v200, v209, v208
	v_div_scale_f32 v211, s[14:15], v75, v75, 1.0
	v_div_fmas_f32 v200, v200, v207, v209
	v_rcp_f32_e32 v212, v211
	v_div_fixup_f32 v74, v200, v74, 1.0
	v_fma_f32 v213, -v211, v212, 1.0
	v_bfe_u32 v200, v74, 16, 1
	v_fmac_f32_e32 v212, v213, v212
	v_add3_u32 v74, v74, v200, s69
	v_div_scale_f32 v213, vcc, 1.0, v75, 1.0
	v_and_b32_e32 v74, 0xffff0000, v74
	v_mul_f32_e32 v214, v213, v212
	v_mul_f32_e32 v76, 0xbfb8aa3b, v44
	v_fma_f32 v215, -v211, v214, v213
	v_exp_f32_e32 v76, v76
	v_fmac_f32_e32 v214, v215, v212
	v_add_f32_e32 v76, 1.0, v76
	v_fma_f32 v211, -v211, v214, v213
	v_div_scale_f32 v200, s[14:15], v76, v76, 1.0
	v_div_fmas_f32 v211, v211, v212, v214
	v_rcp_f32_e32 v207, v200
	v_div_fixup_f32 v75, v211, v75, 1.0
	v_fma_f32 v208, -v200, v207, 1.0
	v_bfe_u32 v211, v75, 16, 1
	v_fmac_f32_e32 v207, v208, v207
	v_add3_u32 v75, v75, v211, s69
	v_div_scale_f32 v208, vcc, 1.0, v76, 1.0
	v_and_b32_e32 v75, 0xffff0000, v75
	v_mul_f32_e32 v209, v208, v207
	v_mul_f32_e32 v77, 0xbfb8aa3b, v45
	v_fma_f32 v210, -v200, v209, v208
	v_exp_f32_e32 v77, v77
	v_fmac_f32_e32 v209, v210, v207
	v_add_f32_e32 v77, 1.0, v77
	v_fma_f32 v200, -v200, v209, v208
	v_div_scale_f32 v211, s[14:15], v77, v77, 1.0
	v_div_fmas_f32 v200, v200, v207, v209
	v_rcp_f32_e32 v212, v211
	v_div_fixup_f32 v76, v200, v76, 1.0
	v_fma_f32 v213, -v211, v212, 1.0
	v_bfe_u32 v200, v76, 16, 1
	v_fmac_f32_e32 v212, v213, v212
	v_add3_u32 v76, v76, v200, s69
	v_div_scale_f32 v213, vcc, 1.0, v77, 1.0
	v_and_b32_e32 v76, 0xffff0000, v76
	v_mul_f32_e32 v214, v213, v212
	v_mul_f32_e32 v78, 0xbfb8aa3b, v46
	v_fma_f32 v215, -v211, v214, v213
	v_exp_f32_e32 v78, v78
	v_fmac_f32_e32 v214, v215, v212
	v_add_f32_e32 v78, 1.0, v78
	v_fma_f32 v211, -v211, v214, v213
	v_div_scale_f32 v200, s[14:15], v78, v78, 1.0
	v_div_fmas_f32 v211, v211, v212, v214
	v_rcp_f32_e32 v207, v200
	v_div_fixup_f32 v77, v211, v77, 1.0
	v_fma_f32 v208, -v200, v207, 1.0
	v_bfe_u32 v211, v77, 16, 1
	v_fmac_f32_e32 v207, v208, v207
	v_add3_u32 v77, v77, v211, s69
	v_div_scale_f32 v208, vcc, 1.0, v78, 1.0
	v_and_b32_e32 v77, 0xffff0000, v77
	v_mul_f32_e32 v209, v208, v207
	v_mul_f32_e32 v79, 0xbfb8aa3b, v47
	v_fma_f32 v210, -v200, v209, v208
	v_exp_f32_e32 v79, v79
	v_fmac_f32_e32 v209, v210, v207
	v_add_f32_e32 v79, 1.0, v79
	v_fma_f32 v200, -v200, v209, v208
	v_div_scale_f32 v211, s[14:15], v79, v79, 1.0
	v_div_fmas_f32 v200, v200, v207, v209
	v_rcp_f32_e32 v212, v211
	v_div_fixup_f32 v78, v200, v78, 1.0
	v_fma_f32 v213, -v211, v212, 1.0
	v_bfe_u32 v200, v78, 16, 1
	v_fmac_f32_e32 v212, v213, v212
	v_add3_u32 v78, v78, v200, s69
	v_div_scale_f32 v213, vcc, 1.0, v79, 1.0
	v_and_b32_e32 v78, 0xffff0000, v78
	v_mul_f32_e32 v214, v213, v212
	v_mul_f32_e32 v80, 0xbfb8aa3b, v48
	v_fma_f32 v215, -v211, v214, v213
	v_exp_f32_e32 v80, v80
	v_fmac_f32_e32 v214, v215, v212
	v_add_f32_e32 v80, 1.0, v80
	v_fma_f32 v211, -v211, v214, v213
	v_div_scale_f32 v200, s[14:15], v80, v80, 1.0
	v_div_fmas_f32 v211, v211, v212, v214
	v_rcp_f32_e32 v207, v200
	v_div_fixup_f32 v79, v211, v79, 1.0
	v_fma_f32 v208, -v200, v207, 1.0
	v_bfe_u32 v211, v79, 16, 1
	v_fmac_f32_e32 v207, v208, v207
	v_add3_u32 v79, v79, v211, s69
	v_div_scale_f32 v208, vcc, 1.0, v80, 1.0
	v_and_b32_e32 v79, 0xffff0000, v79
	v_mul_f32_e32 v209, v208, v207
	v_mul_f32_e32 v81, 0xbfb8aa3b, v49
	v_fma_f32 v210, -v200, v209, v208
	v_exp_f32_e32 v81, v81
	v_fmac_f32_e32 v209, v210, v207
	v_add_f32_e32 v81, 1.0, v81
	v_fma_f32 v200, -v200, v209, v208
	v_div_scale_f32 v211, s[14:15], v81, v81, 1.0
	v_div_fmas_f32 v200, v200, v207, v209
	v_rcp_f32_e32 v212, v211
	v_div_fixup_f32 v80, v200, v80, 1.0
	v_fma_f32 v213, -v211, v212, 1.0
	v_bfe_u32 v200, v80, 16, 1
	v_fmac_f32_e32 v212, v213, v212
	v_add3_u32 v80, v80, v200, s69
	v_div_scale_f32 v213, vcc, 1.0, v81, 1.0
	v_and_b32_e32 v80, 0xffff0000, v80
	v_mul_f32_e32 v214, v213, v212
	v_mul_f32_e32 v82, 0xbfb8aa3b, v50
	v_fma_f32 v215, -v211, v214, v213
	v_exp_f32_e32 v82, v82
	v_fmac_f32_e32 v214, v215, v212
	v_add_f32_e32 v82, 1.0, v82
	v_fma_f32 v211, -v211, v214, v213
	v_div_scale_f32 v200, s[14:15], v82, v82, 1.0
	v_div_fmas_f32 v211, v211, v212, v214
	v_rcp_f32_e32 v207, v200
	v_div_fixup_f32 v81, v211, v81, 1.0
	v_fma_f32 v208, -v200, v207, 1.0
	v_bfe_u32 v211, v81, 16, 1
	v_fmac_f32_e32 v207, v208, v207
	v_add3_u32 v81, v81, v211, s69
	v_div_scale_f32 v208, vcc, 1.0, v82, 1.0
	v_and_b32_e32 v81, 0xffff0000, v81
	v_mul_f32_e32 v209, v208, v207
	v_mul_f32_e32 v83, 0xbfb8aa3b, v51
	v_fma_f32 v210, -v200, v209, v208
	v_exp_f32_e32 v83, v83
	v_fmac_f32_e32 v209, v210, v207
	v_add_f32_e32 v83, 1.0, v83
	v_fma_f32 v200, -v200, v209, v208
	v_div_scale_f32 v211, s[14:15], v83, v83, 1.0
	v_div_fmas_f32 v200, v200, v207, v209
	v_rcp_f32_e32 v212, v211
	v_div_fixup_f32 v82, v200, v82, 1.0
	v_fma_f32 v213, -v211, v212, 1.0
	v_bfe_u32 v200, v82, 16, 1
	v_fmac_f32_e32 v212, v213, v212
	v_add3_u32 v82, v82, v200, s69
	v_div_scale_f32 v213, vcc, 1.0, v83, 1.0
	v_and_b32_e32 v82, 0xffff0000, v82
	v_mul_f32_e32 v214, v213, v212
	v_mul_f32_e32 v84, 0xbfb8aa3b, v52
	v_fma_f32 v215, -v211, v214, v213
	v_exp_f32_e32 v84, v84
	v_fmac_f32_e32 v214, v215, v212
	v_add_f32_e32 v84, 1.0, v84
	v_fma_f32 v211, -v211, v214, v213
	v_div_scale_f32 v200, s[14:15], v84, v84, 1.0
	v_div_fmas_f32 v211, v211, v212, v214
	v_rcp_f32_e32 v207, v200
	v_div_fixup_f32 v83, v211, v83, 1.0
	v_fma_f32 v208, -v200, v207, 1.0
	v_bfe_u32 v211, v83, 16, 1
	v_fmac_f32_e32 v207, v208, v207
	v_add3_u32 v83, v83, v211, s69
	v_div_scale_f32 v208, vcc, 1.0, v84, 1.0
	v_and_b32_e32 v83, 0xffff0000, v83
	v_mul_f32_e32 v209, v208, v207
	v_mul_f32_e32 v85, 0xbfb8aa3b, v53
	v_fma_f32 v210, -v200, v209, v208
	v_exp_f32_e32 v85, v85
	v_fmac_f32_e32 v209, v210, v207
	v_add_f32_e32 v85, 1.0, v85
	v_fma_f32 v200, -v200, v209, v208
	v_div_scale_f32 v211, s[14:15], v85, v85, 1.0
	v_div_fmas_f32 v200, v200, v207, v209
	v_rcp_f32_e32 v212, v211
	v_div_fixup_f32 v84, v200, v84, 1.0
	v_fma_f32 v213, -v211, v212, 1.0
	v_bfe_u32 v200, v84, 16, 1
	v_fmac_f32_e32 v212, v213, v212
	v_add3_u32 v84, v84, v200, s69
	v_div_scale_f32 v213, vcc, 1.0, v85, 1.0
	v_and_b32_e32 v84, 0xffff0000, v84
	v_mul_f32_e32 v214, v213, v212
	v_mul_f32_e32 v86, 0xbfb8aa3b, v54
	v_fma_f32 v215, -v211, v214, v213
	v_exp_f32_e32 v86, v86
	v_fmac_f32_e32 v214, v215, v212
	v_add_f32_e32 v86, 1.0, v86
	v_fma_f32 v211, -v211, v214, v213
	v_div_scale_f32 v200, s[14:15], v86, v86, 1.0
	v_div_fmas_f32 v211, v211, v212, v214
	v_rcp_f32_e32 v207, v200
	v_div_fixup_f32 v85, v211, v85, 1.0
	v_fma_f32 v208, -v200, v207, 1.0
	v_bfe_u32 v211, v85, 16, 1
	v_fmac_f32_e32 v207, v208, v207
	v_add3_u32 v85, v85, v211, s69
	v_div_scale_f32 v208, vcc, 1.0, v86, 1.0
	v_and_b32_e32 v85, 0xffff0000, v85
	v_mul_f32_e32 v209, v208, v207
	v_mul_f32_e32 v87, 0xbfb8aa3b, v55
	v_fma_f32 v210, -v200, v209, v208
	v_exp_f32_e32 v87, v87
	v_fmac_f32_e32 v209, v210, v207
	v_add_f32_e32 v87, 1.0, v87
	v_fma_f32 v200, -v200, v209, v208
	v_div_scale_f32 v211, s[14:15], v87, v87, 1.0
	v_div_fmas_f32 v200, v200, v207, v209
	v_rcp_f32_e32 v212, v211
	v_div_fixup_f32 v86, v200, v86, 1.0
	v_fma_f32 v213, -v211, v212, 1.0
	v_bfe_u32 v200, v86, 16, 1
	v_fmac_f32_e32 v212, v213, v212
	v_add3_u32 v86, v86, v200, s69
	v_div_scale_f32 v213, vcc, 1.0, v87, 1.0
	v_and_b32_e32 v86, 0xffff0000, v86
	v_mul_f32_e32 v214, v213, v212
	v_mul_f32_e32 v88, 0xbfb8aa3b, v56
	v_fma_f32 v215, -v211, v214, v213
	v_exp_f32_e32 v88, v88
	v_fmac_f32_e32 v214, v215, v212
	v_add_f32_e32 v88, 1.0, v88
	v_fma_f32 v211, -v211, v214, v213
	v_div_scale_f32 v200, s[14:15], v88, v88, 1.0
	v_div_fmas_f32 v211, v211, v212, v214
	v_rcp_f32_e32 v207, v200
	v_div_fixup_f32 v87, v211, v87, 1.0
	v_fma_f32 v208, -v200, v207, 1.0
	v_bfe_u32 v211, v87, 16, 1
	v_fmac_f32_e32 v207, v208, v207
	v_add3_u32 v87, v87, v211, s69
	v_div_scale_f32 v208, vcc, 1.0, v88, 1.0
	v_and_b32_e32 v87, 0xffff0000, v87
	v_mul_f32_e32 v209, v208, v207
	v_mul_f32_e32 v89, 0xbfb8aa3b, v57
	v_fma_f32 v210, -v200, v209, v208
	v_exp_f32_e32 v89, v89
	v_fmac_f32_e32 v209, v210, v207
	v_add_f32_e32 v89, 1.0, v89
	v_fma_f32 v200, -v200, v209, v208
	v_div_scale_f32 v211, s[14:15], v89, v89, 1.0
	v_div_fmas_f32 v200, v200, v207, v209
	v_rcp_f32_e32 v212, v211
	v_div_fixup_f32 v88, v200, v88, 1.0
	v_fma_f32 v213, -v211, v212, 1.0
	v_bfe_u32 v200, v88, 16, 1
	v_fmac_f32_e32 v212, v213, v212
	v_add3_u32 v88, v88, v200, s69
	v_div_scale_f32 v213, vcc, 1.0, v89, 1.0
	v_and_b32_e32 v88, 0xffff0000, v88
	v_mul_f32_e32 v214, v213, v212
	v_mul_f32_e32 v90, 0xbfb8aa3b, v58
	v_fma_f32 v215, -v211, v214, v213
	v_exp_f32_e32 v90, v90
	v_fmac_f32_e32 v214, v215, v212
	v_add_f32_e32 v90, 1.0, v90
	v_fma_f32 v211, -v211, v214, v213
	v_div_scale_f32 v200, s[14:15], v90, v90, 1.0
	v_div_fmas_f32 v211, v211, v212, v214
	v_rcp_f32_e32 v207, v200
	v_div_fixup_f32 v89, v211, v89, 1.0
	v_fma_f32 v208, -v200, v207, 1.0
	v_bfe_u32 v211, v89, 16, 1
	v_fmac_f32_e32 v207, v208, v207
	v_add3_u32 v89, v89, v211, s69
	v_div_scale_f32 v208, vcc, 1.0, v90, 1.0
	v_and_b32_e32 v89, 0xffff0000, v89
	v_mul_f32_e32 v209, v208, v207
	v_mul_f32_e32 v91, 0xbfb8aa3b, v59
	v_fma_f32 v210, -v200, v209, v208
	v_exp_f32_e32 v91, v91
	v_fmac_f32_e32 v209, v210, v207
	v_add_f32_e32 v91, 1.0, v91
	v_fma_f32 v200, -v200, v209, v208
	v_div_scale_f32 v211, s[14:15], v91, v91, 1.0
	v_div_fmas_f32 v200, v200, v207, v209
	v_rcp_f32_e32 v212, v211
	v_div_fixup_f32 v90, v200, v90, 1.0
	v_fma_f32 v213, -v211, v212, 1.0
	v_bfe_u32 v200, v90, 16, 1
	v_fmac_f32_e32 v212, v213, v212
	v_add3_u32 v90, v90, v200, s69
	v_div_scale_f32 v213, vcc, 1.0, v91, 1.0
	v_and_b32_e32 v90, 0xffff0000, v90
	v_mul_f32_e32 v214, v213, v212
	v_mul_f32_e32 v92, 0xbfb8aa3b, v60
	v_fma_f32 v215, -v211, v214, v213
	v_exp_f32_e32 v92, v92
	v_fmac_f32_e32 v214, v215, v212
	v_add_f32_e32 v92, 1.0, v92
	v_fma_f32 v211, -v211, v214, v213
	v_div_scale_f32 v200, s[14:15], v92, v92, 1.0
	v_div_fmas_f32 v211, v211, v212, v214
	v_rcp_f32_e32 v207, v200
	v_div_fixup_f32 v91, v211, v91, 1.0
	v_fma_f32 v208, -v200, v207, 1.0
	v_bfe_u32 v211, v91, 16, 1
	v_fmac_f32_e32 v207, v208, v207
	v_add3_u32 v91, v91, v211, s69
	v_div_scale_f32 v208, vcc, 1.0, v92, 1.0
	v_and_b32_e32 v91, 0xffff0000, v91
	v_mul_f32_e32 v209, v208, v207
	v_mul_f32_e32 v93, 0xbfb8aa3b, v61
	v_fma_f32 v210, -v200, v209, v208
	v_exp_f32_e32 v93, v93
	v_fmac_f32_e32 v209, v210, v207
	v_add_f32_e32 v93, 1.0, v93
	v_fma_f32 v200, -v200, v209, v208
	v_div_scale_f32 v211, s[14:15], v93, v93, 1.0
	v_div_fmas_f32 v200, v200, v207, v209
	v_rcp_f32_e32 v212, v211
	v_div_fixup_f32 v92, v200, v92, 1.0
	v_fma_f32 v213, -v211, v212, 1.0
	v_bfe_u32 v200, v92, 16, 1
	v_fmac_f32_e32 v212, v213, v212
	v_add3_u32 v92, v92, v200, s69
	v_div_scale_f32 v213, vcc, 1.0, v93, 1.0
	v_and_b32_e32 v92, 0xffff0000, v92
	v_mul_f32_e32 v214, v213, v212
	v_mul_f32_e32 v94, 0xbfb8aa3b, v62
	v_fma_f32 v215, -v211, v214, v213
	v_exp_f32_e32 v94, v94
	v_fmac_f32_e32 v214, v215, v212
	v_add_f32_e32 v94, 1.0, v94
	v_fma_f32 v211, -v211, v214, v213
	v_div_scale_f32 v200, s[14:15], v94, v94, 1.0
	v_div_fmas_f32 v211, v211, v212, v214
	v_rcp_f32_e32 v207, v200
	v_div_fixup_f32 v93, v211, v93, 1.0
	v_fma_f32 v208, -v200, v207, 1.0
	v_bfe_u32 v211, v93, 16, 1
	v_fmac_f32_e32 v207, v208, v207
	v_add3_u32 v93, v93, v211, s69
	v_div_scale_f32 v208, vcc, 1.0, v94, 1.0
	v_and_b32_e32 v93, 0xffff0000, v93
	v_mul_f32_e32 v209, v208, v207
	v_mul_f32_e32 v95, 0xbfb8aa3b, v63
	v_fma_f32 v210, -v200, v209, v208
	v_exp_f32_e32 v95, v95
	v_fmac_f32_e32 v209, v210, v207
	v_add_f32_e32 v95, 1.0, v95
	v_fma_f32 v200, -v200, v209, v208
	v_div_scale_f32 v211, s[14:15], v95, v95, 1.0
	v_div_fmas_f32 v200, v200, v207, v209
	v_rcp_f32_e32 v212, v211
	v_div_fixup_f32 v94, v200, v94, 1.0
	v_fma_f32 v213, -v211, v212, 1.0
	v_bfe_u32 v200, v94, 16, 1
	v_fmac_f32_e32 v212, v213, v212
	v_add3_u32 v94, v94, v200, s69
	v_div_scale_f32 v213, vcc, 1.0, v95, 1.0
	v_and_b32_e32 v94, 0xffff0000, v94
	v_mul_f32_e32 v214, v213, v212
	v_fma_f32 v215, -v211, v214, v213
	s_nop 0
	v_fmac_f32_e32 v214, v215, v212
	s_nop 0
	v_fma_f32 v211, -v211, v214, v213
	s_nop 0
	v_div_fmas_f32 v211, v211, v212, v214
	s_nop 0
	v_div_fixup_f32 v95, v211, v95, 1.0
	s_nop 0
	v_bfe_u32 v211, v95, 16, 1
	s_nop 0
	v_add3_u32 v95, v95, v211, s69
	s_nop 0
	v_and_b32_e32 v95, 0xffff0000, v95
	s_nop 0
	v_mov_b32_e32 v32, 0
	v_mov_b32_e32 v33, 0
	v_mov_b32_e32 v34, 0
	v_mov_b32_e32 v35, 0
	v_mov_b32_e32 v36, 0
	v_mov_b32_e32 v37, 0
	v_mov_b32_e32 v38, 0
	v_mov_b32_e32 v39, 0
	v_mov_b32_e32 v40, 0
	v_mov_b32_e32 v41, 0
	v_mov_b32_e32 v42, 0
	v_mov_b32_e32 v43, 0
	v_mov_b32_e32 v44, 0
	v_mov_b32_e32 v45, 0
	v_mov_b32_e32 v46, 0
	v_mov_b32_e32 v47, 0
	v_mov_b32_e32 v48, 0
	v_mov_b32_e32 v49, 0
	v_mov_b32_e32 v50, 0
	v_mov_b32_e32 v51, 0
	v_mov_b32_e32 v52, 0
	v_mov_b32_e32 v53, 0
	v_mov_b32_e32 v54, 0
	v_mov_b32_e32 v55, 0
	v_mov_b32_e32 v56, 0
	v_mov_b32_e32 v57, 0
	v_mov_b32_e32 v58, 0
	v_mov_b32_e32 v59, 0
	v_mov_b32_e32 v60, 0
	v_mov_b32_e32 v61, 0
	v_mov_b32_e32 v62, 0
	v_mov_b32_e32 v63, 0
	s_waitcnt vmcnt(0)
	s_barrier
	v_mfma_f32_16x16x32_bf16 v[32:35], v[128:131], v[96:99], v[32:35]
	s_add_u32 m0, s12, 0x0
	ds_read_b128 v[144:147], v203 offset:24576
	v_mfma_f32_16x16x32_bf16 v[36:39], v[132:135], v[96:99], v[36:39]
	global_load_lds_dwordx4 v192, s[8:9]
	s_add_u32 m0, s12, 0x400
	ds_read_b128 v[148:151], v203 offset:26624
	v_mfma_f32_16x16x32_bf16 v[40:43], v[128:131], v[100:103], v[40:43]
	global_load_lds_dwordx4 v193, s[8:9]
	s_add_u32 m0, s12, 0x800
	ds_read_b128 v[152:155], v203 offset:28672
	v_mfma_f32_16x16x32_bf16 v[44:47], v[132:135], v[100:103], v[44:47]
	global_load_lds_dwordx4 v194, s[8:9]
	s_add_u32 m0, s12, 0xc00
	ds_read_b128 v[156:159], v203 offset:30720
	v_mfma_f32_16x16x32_bf16 v[48:51], v[128:131], v[104:107], v[48:51]
	global_load_lds_dwordx4 v195, s[8:9]
	s_add_u32 m0, s13, 0x4000
	ds_read_b128 v[176:179], v205 offset:40960
	v_mfma_f32_16x16x32_bf16 v[52:55], v[132:135], v[104:107], v[52:55]
	global_load_lds_dwordx4 v198, s[10:11]
	s_add_u32 m0, s13, 0x4400
	ds_read_b128 v[180:183], v205 offset:43008
	v_mfma_f32_16x16x32_bf16 v[56:59], v[128:131], v[108:111], v[56:59]
	global_load_lds_dwordx4 v199, s[10:11]
	ds_read_b128 v[160:163], v204 offset:24576
	v_mfma_f32_16x16x32_bf16 v[60:63], v[132:135], v[108:111], v[60:63]
	s_add_u32 s8, s8, 0x80
	s_addc_u32 s9, s9, 0
	ds_read_b128 v[164:167], v204 offset:26624
	v_mfma_f32_16x16x32_bf16 v[32:35], v[136:139], v[112:115], v[32:35]
	s_add_u32 s10, s10, 0x80
	s_addc_u32 s11, s11, 0
	ds_read_b128 v[168:171], v204 offset:28672
	v_mfma_f32_16x16x32_bf16 v[36:39], v[140:143], v[112:115], v[36:39]
	ds_read_b128 v[172:175], v204 offset:30720
	v_mfma_f32_16x16x32_bf16 v[40:43], v[136:139], v[116:119], v[40:43]
	ds_read_b128 v[184:187], v206 offset:40960
	v_mfma_f32_16x16x32_bf16 v[44:47], v[140:143], v[116:119], v[44:47]
	ds_read_b128 v[188:191], v206 offset:43008
	v_mfma_f32_16x16x32_bf16 v[48:51], v[136:139], v[120:123], v[48:51]
	v_mfma_f32_16x16x32_bf16 v[52:55], v[140:143], v[120:123], v[52:55]
	v_mfma_f32_16x16x32_bf16 v[56:59], v[136:139], v[124:127], v[56:59]
	v_mfma_f32_16x16x32_bf16 v[60:63], v[140:143], v[124:127], v[60:63]
	s_waitcnt lgkmcnt(0)
	s_waitcnt vmcnt(0)
	s_barrier
	v_mfma_f32_16x16x32_bf16 v[32:35], v[176:179], v[144:147], v[32:35]
	s_add_u32 m0, s12, 0x6000
	ds_read_b128 v[96:99], v203 offset:0
	v_mfma_f32_16x16x32_bf16 v[36:39], v[180:183], v[144:147], v[36:39]
	global_load_lds_dwordx4 v192, s[8:9]
	s_add_u32 m0, s12, 0x6400
	ds_read_b128 v[100:103], v203 offset:2048
	v_mfma_f32_16x16x32_bf16 v[40:43], v[176:179], v[148:151], v[40:43]
	global_load_lds_dwordx4 v193, s[8:9]
	s_add_u32 m0, s12, 0x6800
	ds_read_b128 v[104:107], v203 offset:4096
	v_mfma_f32_16x16x32_bf16 v[44:47], v[180:183], v[148:151], v[44:47]
	global_load_lds_dwordx4 v194, s[8:9]
	s_add_u32 m0, s12, 0x6c00
	ds_read_b128 v[108:111], v203 offset:6144
	v_mfma_f32_16x16x32_bf16 v[48:51], v[176:179], v[152:155], v[48:51]
	global_load_lds_dwordx4 v195, s[8:9]
	s_add_u32 m0, s13, 0xa000
	ds_read_b128 v[128:131], v205 offset:16384
	v_mfma_f32_16x16x32_bf16 v[52:55], v[180:183], v[152:155], v[52:55]
	global_load_lds_dwordx4 v198, s[10:11]
	s_add_u32 m0, s13, 0xa400
	ds_read_b128 v[132:135], v205 offset:18432
	v_mfma_f32_16x16x32_bf16 v[56:59], v[176:179], v[156:159], v[56:59]
	global_load_lds_dwordx4 v199, s[10:11]
	ds_read_b128 v[112:115], v204 offset:0
	v_mfma_f32_16x16x32_bf16 v[60:63], v[180:183], v[156:159], v[60:63]
	s_add_u32 s8, s8, 0x80
	s_addc_u32 s9, s9, 0
	ds_read_b128 v[116:119], v204 offset:2048
	v_mfma_f32_16x16x32_bf16 v[32:35], v[184:187], v[160:163], v[32:35]
	s_add_u32 s10, s10, 0x80
	s_addc_u32 s11, s11, 0
	ds_read_b128 v[120:123], v204 offset:4096
	v_mfma_f32_16x16x32_bf16 v[36:39], v[188:191], v[160:163], v[36:39]
	s_add_u32 s10, s10, 0x7fe00
	s_addc_u32 s11, s11, 0
	ds_read_b128 v[124:127], v204 offset:6144
	v_mfma_f32_16x16x32_bf16 v[40:43], v[184:187], v[164:167], v[40:43]
	ds_read_b128 v[136:139], v206 offset:16384
	v_mfma_f32_16x16x32_bf16 v[44:47], v[188:191], v[164:167], v[44:47]
	ds_read_b128 v[140:143], v206 offset:18432
	v_mfma_f32_16x16x32_bf16 v[48:51], v[184:187], v[168:171], v[48:51]
	v_mfma_f32_16x16x32_bf16 v[52:55], v[188:191], v[168:171], v[52:55]
	v_mfma_f32_16x16x32_bf16 v[56:59], v[184:187], v[172:175], v[56:59]
	v_mfma_f32_16x16x32_bf16 v[60:63], v[188:191], v[172:175], v[60:63]
	s_waitcnt lgkmcnt(0)
	s_cmp_eq_u32 s17, 3
	s_cbranch_scc1 .Lg4_last
	s_waitcnt vmcnt(0)
	s_barrier
	v_mfma_f32_16x16x32_bf16 v[32:35], v[128:131], v[96:99], v[32:35]
	s_add_u32 m0, s12, 0x0
	ds_read_b128 v[144:147], v203 offset:24576
	v_mfma_f32_16x16x32_bf16 v[36:39], v[132:135], v[96:99], v[36:39]
	global_load_lds_dwordx4 v246, s[2:3]
	s_add_u32 m0, s12, 0x400
	ds_read_b128 v[148:151], v203 offset:26624
	v_mfma_f32_16x16x32_bf16 v[40:43], v[128:131], v[100:103], v[40:43]
	global_load_lds_dwordx4 v247, s[2:3]
	s_add_u32 m0, s12, 0x800
	ds_read_b128 v[152:155], v203 offset:28672
	v_mfma_f32_16x16x32_bf16 v[44:47], v[132:135], v[100:103], v[44:47]
	global_load_lds_dwordx4 v248, s[2:3]
	s_add_u32 m0, s12, 0xc00
	ds_read_b128 v[156:159], v203 offset:30720
	v_mfma_f32_16x16x32_bf16 v[48:51], v[128:131], v[104:107], v[48:51]
	global_load_lds_dwordx4 v249, s[2:3]
	s_add_u32 m0, s13, 0x4000
	ds_read_b128 v[176:179], v205 offset:40960
	v_mfma_f32_16x16x32_bf16 v[52:55], v[132:135], v[104:107], v[52:55]
	global_load_lds_dwordx4 v196, s[4:5]
	s_add_u32 m0, s13, 0x4400
	ds_read_b128 v[180:183], v205 offset:43008
	v_mfma_f32_16x16x32_bf16 v[56:59], v[128:131], v[108:111], v[56:59]
	global_load_lds_dwordx4 v197, s[4:5]
	ds_read_b128 v[160:163], v204 offset:24576
	v_mfma_f32_16x16x32_bf16 v[60:63], v[132:135], v[108:111], v[60:63]
	s_add_u32 s2, s2, 0x4000
	s_addc_u32 s3, s3, 0
	ds_read_b128 v[164:167], v204 offset:26624
	v_mfma_f32_16x16x32_bf16 v[32:35], v[136:139], v[112:115], v[32:35]
	s_add_u32 s4, s4, 0x80
	s_addc_u32 s5, s5, 0
	ds_read_b128 v[168:171], v204 offset:28672
	v_mfma_f32_16x16x32_bf16 v[36:39], v[140:143], v[112:115], v[36:39]
	ds_read_b128 v[172:175], v204 offset:30720
	v_mfma_f32_16x16x32_bf16 v[40:43], v[136:139], v[116:119], v[40:43]
	ds_read_b128 v[184:187], v206 offset:40960
	v_mfma_f32_16x16x32_bf16 v[44:47], v[140:143], v[116:119], v[44:47]
	ds_read_b128 v[188:191], v206 offset:43008
	v_mfma_f32_16x16x32_bf16 v[48:51], v[136:139], v[120:123], v[48:51]
	v_mfma_f32_16x16x32_bf16 v[52:55], v[140:143], v[120:123], v[52:55]
	v_mfma_f32_16x16x32_bf16 v[56:59], v[136:139], v[124:127], v[56:59]
	v_mfma_f32_16x16x32_bf16 v[60:63], v[140:143], v[124:127], v[60:63]
	s_waitcnt lgkmcnt(0)
	s_waitcnt vmcnt(0)
	s_barrier
	v_mfma_f32_16x16x32_bf16 v[32:35], v[176:179], v[144:147], v[32:35]
	s_add_u32 m0, s12, 0x6000
	ds_read_b128 v[96:99], v203 offset:0
	v_mfma_f32_16x16x32_bf16 v[36:39], v[180:183], v[144:147], v[36:39]
	global_load_lds_dwordx4 v246, s[2:3]
	s_add_u32 m0, s12, 0x6400
	ds_read_b128 v[100:103], v203 offset:2048
	v_mfma_f32_16x16x32_bf16 v[40:43], v[176:179], v[148:151], v[40:43]
	global_load_lds_dwordx4 v247, s[2:3]
	s_add_u32 m0, s12, 0x6800
	ds_read_b128 v[104:107], v203 offset:4096
	v_mfma_f32_16x16x32_bf16 v[44:47], v[180:183], v[148:151], v[44:47]
	global_load_lds_dwordx4 v248, s[2:3]
	s_add_u32 m0, s12, 0x6c00
	ds_read_b128 v[108:111], v203 offset:6144
	v_mfma_f32_16x16x32_bf16 v[48:51], v[176:179], v[152:155], v[48:51]
	global_load_lds_dwordx4 v249, s[2:3]
	s_add_u32 m0, s13, 0xa000
	ds_read_b128 v[128:131], v205 offset:16384
	v_mfma_f32_16x16x32_bf16 v[52:55], v[180:183], v[152:155], v[52:55]
	global_load_lds_dwordx4 v196, s[4:5]
	s_add_u32 m0, s13, 0xa400
	ds_read_b128 v[132:135], v205 offset:18432
	v_mfma_f32_16x16x32_bf16 v[56:59], v[176:179], v[156:159], v[56:59]
	global_load_lds_dwordx4 v197, s[4:5]
	ds_read_b128 v[112:115], v204 offset:0
	v_mfma_f32_16x16x32_bf16 v[60:63], v[180:183], v[156:159], v[60:63]
	s_add_u32 s2, s2, 0x4000
	s_addc_u32 s3, s3, 0
	ds_read_b128 v[116:119], v204 offset:2048
	v_mfma_f32_16x16x32_bf16 v[32:35], v[184:187], v[160:163], v[32:35]
	s_add_u32 s4, s4, 0x80
	s_addc_u32 s5, s5, 0
	ds_read_b128 v[120:123], v204 offset:4096
	v_mfma_f32_16x16x32_bf16 v[36:39], v[188:191], v[160:163], v[36:39]
	ds_read_b128 v[124:127], v204 offset:6144
	v_mfma_f32_16x16x32_bf16 v[40:43], v[184:187], v[164:167], v[40:43]
	ds_read_b128 v[136:139], v206 offset:16384
	v_mfma_f32_16x16x32_bf16 v[44:47], v[188:191], v[164:167], v[44:47]
	ds_read_b128 v[140:143], v206 offset:18432
	v_mfma_f32_16x16x32_bf16 v[48:51], v[184:187], v[168:171], v[48:51]
	v_mfma_f32_16x16x32_bf16 v[52:55], v[188:191], v[168:171], v[52:55]
	v_mfma_f32_16x16x32_bf16 v[56:59], v[184:187], v[172:175], v[56:59]
	v_mfma_f32_16x16x32_bf16 v[60:63], v[188:191], v[172:175], v[60:63]
	s_waitcnt lgkmcnt(0)
	s_nop 7
	s_nop 1
	v_pk_fma_f32 v[0:1], v[32:33], v[64:65], v[0:1]
	v_pk_fma_f32 v[2:3], v[34:35], v[66:67], v[2:3]
	v_pk_fma_f32 v[4:5], v[36:37], v[68:69], v[4:5]
	v_pk_fma_f32 v[6:7], v[38:39], v[70:71], v[6:7]
	v_pk_fma_f32 v[8:9], v[40:41], v[72:73], v[8:9]
	v_pk_fma_f32 v[10:11], v[42:43], v[74:75], v[10:11]
	v_pk_fma_f32 v[12:13], v[44:45], v[76:77], v[12:13]
	v_pk_fma_f32 v[14:15], v[46:47], v[78:79], v[14:15]
	v_pk_fma_f32 v[16:17], v[48:49], v[80:81], v[16:17]
	v_pk_fma_f32 v[18:19], v[50:51], v[82:83], v[18:19]
	v_pk_fma_f32 v[20:21], v[52:53], v[84:85], v[20:21]
	v_pk_fma_f32 v[22:23], v[54:55], v[86:87], v[22:23]
	v_pk_fma_f32 v[24:25], v[56:57], v[88:89], v[24:25]
	v_pk_fma_f32 v[26:27], v[58:59], v[90:91], v[26:27]
	v_pk_fma_f32 v[28:29], v[60:61], v[92:93], v[28:29]
	v_pk_fma_f32 v[30:31], v[62:63], v[94:95], v[30:31]
	v_mov_b32_e32 v32, 0
	v_mov_b32_e32 v33, 0
	v_mov_b32_e32 v34, 0
	v_mov_b32_e32 v35, 0
	v_mov_b32_e32 v36, 0
	v_mov_b32_e32 v37, 0
	v_mov_b32_e32 v38, 0
	v_mov_b32_e32 v39, 0
	v_mov_b32_e32 v40, 0
	v_mov_b32_e32 v41, 0
	v_mov_b32_e32 v42, 0
	v_mov_b32_e32 v43, 0
	v_mov_b32_e32 v44, 0
	v_mov_b32_e32 v45, 0
	v_mov_b32_e32 v46, 0
	v_mov_b32_e32 v47, 0
	v_mov_b32_e32 v48, 0
	v_mov_b32_e32 v49, 0
	v_mov_b32_e32 v50, 0
	v_mov_b32_e32 v51, 0
	v_mov_b32_e32 v52, 0
	v_mov_b32_e32 v53, 0
	v_mov_b32_e32 v54, 0
	v_mov_b32_e32 v55, 0
	v_mov_b32_e32 v56, 0
	v_mov_b32_e32 v57, 0
	v_mov_b32_e32 v58, 0
	v_mov_b32_e32 v59, 0
	v_mov_b32_e32 v60, 0
	v_mov_b32_e32 v61, 0
	v_mov_b32_e32 v62, 0
	v_mov_b32_e32 v63, 0
	s_add_u32 s17, s17, 1
	s_branch .Lg4_nloop
